# GEMM K-loops: closing barrier reached before s_setprio 0 (one issue slot earlier hand-off)
# baseline (speedup 1.0000x reference)
; #define PG8_STAGE(bufoff, gbase, voff) do { _Pragma("unroll") for (int _i = 0; _i < 2; ++_i) \
;         __builtin_amdgcn_global_load_lds((const unsigned*)((const char*)(gbase) + (voff)[_i]), (PG8_LAS unsigned*)(lds + (bufoff) + ldsw + _i * 8192), 16, 0, 0); } while (0)
; #define PG8_LDA(dst, b, h) do { _Pragma("unroll") for (int m = 0; m < 4; ++m) _Pragma("unroll") for (int k = 0; k < 2; ++k) dst[m][k] = *(const PG8_LAS bf16x8*)(lds + PG8_SA(b, h) + aoff + m * 2048 + k * 1024); } while (0)
; #define PG8_LDB(dst, b, h) do { _Pragma("unroll") for (int n = 0; n < 2; ++n) _Pragma("unroll") for (int k = 0; k < 2; ++k) dst[n][k] = *(const PG8_LAS bf16x8*)(lds + PG8_SB(b, h) + boff + n * 2048 + k * 1024); } while (0)
; #define PG8_MMA(ai, bj, At, Bt) do { __builtin_amdgcn_s_setprio(1); _Pragma("unroll") for (int m = 0; m < 4; ++m) _Pragma("unroll") for (int n = 0; n < 2; ++n) _Pragma("unroll") for (int k = 0; k < 2; ++k) \
;         acc[ai][bj][m][n] = __builtin_amdgcn_mfma_f32_16x16x32_bf16(Bt[n][k], At[m][k], acc[ai][bj][m][n], 0, 0, 0); __builtin_amdgcn_s_setprio(0); } while (0)
; template <class Epi, class Sched, bool ALIGN_EPI = false, bool SP2 = false>
; __device__ __forceinline__ void gemm_phase(PG8_LAS unsigned char* lds, const Gemm g, const Sched& S, const Epi& E, const int wv) {
;     ...
;             if constexpr (SP2) {
;             PG8_LDB(B0, 0, 0); PG8_LDB(B1, 0, 1); PG8_SCHED; PG8_LDA(At, 0, 0); PG8_STAGE(PG8_SA(1, 1), a1 + hstep, voffA);
;             PG8_WAIT_V(8); PG8_WAIT_L(0); PG8_BAR; PG8_MMA(0, 0, At, B0); PG8_MMA(0, 1, At, B1); PG8_BAR; PG8_SCHED;
;             PG8_LDA(At, 0, 1); PG8_STAGE(PG8_SB(0, 0), b2, voffB); PG8_STAGE(PG8_SB(0, 1), b2 + hstep, voffB); PG8_STAGE(PG8_SA(0, 0), a2, voffA);
;             PG8_WAIT_V(8); PG8_WAIT_L(0); PG8_BAR; PG8_MMA(1, 0, At, B0); PG8_MMA(1, 1, At, B1); PG8_BAR; PG8_SCHED;
;             PG8_LDB(B0, 1, 0); PG8_LDB(B1, 1, 1); PG8_SCHED; PG8_LDA(At, 1, 0); PG8_STAGE(PG8_SA(0, 1), a2 + hstep, voffA);
;             PG8_WAIT_V(8); PG8_WAIT_L(0); PG8_BAR; PG8_MMA(0, 0, At, B0); PG8_MMA(0, 1, At, B1); PG8_BAR; PG8_SCHED;
;             PG8_LDA(At, 1, 1); PG8_STAGE(PG8_SB(1, 0), b3, voffB); PG8_STAGE(PG8_SB(1, 1), b3 + hstep, voffB); PG8_STAGE(PG8_SA(1, 0), a3, voffA);
;             PG8_WAIT_V(8); PG8_WAIT_L(0); PG8_BAR; PG8_MMA(1, 0, At, B0); PG8_MMA(1, 1, At, B1); PG8_BAR; PG8_SCHED;
.LBB0_40:
	s_add_u32 s74, s76, 0xffe00080
	s_addc_u32 s75, s77, -1
	s_add_i32 s82, 0, 0x10000
	s_cmpk_eq_i32 s66, 0x7c
	s_cselect_b32 s81, s34, s75
	s_cselect_b32 s80, s35, s74
	v_add_u32_e32 v146, s82, v154
	s_cselect_b32 s79, s47, s62
	s_cselect_b32 s78, s49, s61
	s_add_i32 s83, 0, 0x14000
	ds_read_b128 v[142:145], v146
	ds_read_b128 v[158:161], v146 offset:1024
	ds_read_b128 v[162:165], v146 offset:2048
	ds_read_b128 v[166:169], v146 offset:3072
	v_add_u32_e32 v146, s83, v154
	ds_read_b128 v[170:173], v146
	ds_read_b128 v[174:177], v146 offset:1024
	ds_read_b128 v[190:193], v146 offset:2048
	ds_read_b128 v[194:197], v146 offset:3072
	v_lshl_add_u64 v[146:147], s[76:77], 0, v[140:141]
	s_add_i32 m0, s14, 0xc000
	ds_read_b128 v[198:201], v156
	ds_read_b128 v[202:205], v156 offset:1024
	ds_read_b128 v[206:209], v156 offset:2048
	ds_read_b128 v[210:213], v156 offset:3072
	ds_read_b128 v[214:217], v156 offset:4096
	ds_read_b128 v[218:221], v156 offset:5120
	ds_read_b128 v[222:225], v156 offset:6144
	ds_read_b128 v[226:229], v156 offset:7168
	global_load_lds_dwordx4 v[146:147], off
	v_lshl_add_u64 v[146:147], s[76:77], 0, v[138:139]
	s_add_i32 m0, s14, 0xe000
	s_nop 0
	global_load_lds_dwordx4 v[146:147], off
	s_waitcnt vmcnt(8)
	s_waitcnt lgkmcnt(0)
	s_setprio 1
	s_barrier
	v_mfma_f32_16x16x32_bf16 v[126:129], v[142:145], v[198:201], v[126:129]
	v_mfma_f32_16x16x32_bf16 v[122:125], v[162:165], v[198:201], v[122:125]
	v_mfma_f32_16x16x32_bf16 v[110:113], v[142:145], v[206:209], v[110:113]
	v_mfma_f32_16x16x32_bf16 v[106:109], v[162:165], v[206:209], v[106:109]
	v_mfma_f32_16x16x32_bf16 v[94:97], v[142:145], v[214:217], v[94:97]
	v_mfma_f32_16x16x32_bf16 v[90:93], v[162:165], v[214:217], v[90:93]
	v_mfma_f32_16x16x32_bf16 v[78:81], v[142:145], v[222:225], v[78:81]
	v_mfma_f32_16x16x32_bf16 v[74:77], v[162:165], v[222:225], v[74:77]
	v_mfma_f32_16x16x32_bf16 v[126:129], v[158:161], v[202:205], v[126:129]
	v_mfma_f32_16x16x32_bf16 v[122:125], v[166:169], v[202:205], v[122:125]
	v_mfma_f32_16x16x32_bf16 v[110:113], v[158:161], v[210:213], v[110:113]
	v_mfma_f32_16x16x32_bf16 v[106:109], v[166:169], v[210:213], v[106:109]
	v_mfma_f32_16x16x32_bf16 v[94:97], v[158:161], v[218:221], v[94:97]
	v_mfma_f32_16x16x32_bf16 v[90:93], v[166:169], v[218:221], v[90:93]
	v_mfma_f32_16x16x32_bf16 v[78:81], v[158:161], v[226:229], v[78:81]
	v_mfma_f32_16x16x32_bf16 v[74:77], v[166:169], v[226:229], v[74:77]
	v_mfma_f32_16x16x32_bf16 v[118:121], v[170:173], v[198:201], v[118:121]
	v_mfma_f32_16x16x32_bf16 v[114:117], v[190:193], v[198:201], v[114:117]
	v_mfma_f32_16x16x32_bf16 v[102:105], v[170:173], v[206:209], v[102:105]
	v_mfma_f32_16x16x32_bf16 v[98:101], v[190:193], v[206:209], v[98:101]
	v_mfma_f32_16x16x32_bf16 v[86:89], v[170:173], v[214:217], v[86:89]
	v_mfma_f32_16x16x32_bf16 v[82:85], v[190:193], v[214:217], v[82:85]
	v_mfma_f32_16x16x32_bf16 v[70:73], v[170:173], v[222:225], v[70:73]
	v_mfma_f32_16x16x32_bf16 v[66:69], v[190:193], v[222:225], v[66:69]
	v_mfma_f32_16x16x32_bf16 v[118:121], v[174:177], v[202:205], v[118:121]
	v_mfma_f32_16x16x32_bf16 v[114:117], v[194:197], v[202:205], v[114:117]
	v_mfma_f32_16x16x32_bf16 v[102:105], v[174:177], v[210:213], v[102:105]
	v_mfma_f32_16x16x32_bf16 v[98:101], v[194:197], v[210:213], v[98:101]
	v_mfma_f32_16x16x32_bf16 v[86:89], v[174:177], v[218:221], v[86:89]
	v_mfma_f32_16x16x32_bf16 v[82:85], v[194:197], v[218:221], v[82:85]
	v_mfma_f32_16x16x32_bf16 v[70:73], v[174:177], v[226:229], v[70:73]
	v_mfma_f32_16x16x32_bf16 v[66:69], v[194:197], v[226:229], v[66:69]
	s_barrier
	s_setprio 0
	s_add_i32 s74, s82, s7
	v_lshl_add_u64 v[146:147], s[78:79], 0, v[134:135]
	s_mov_b32 m0, s74
	ds_read_b128 v[198:201], v156 offset:16384
	ds_read_b128 v[202:205], v156 offset:17408
	ds_read_b128 v[206:209], v156 offset:18432
	ds_read_b128 v[210:213], v156 offset:19456
	ds_read_b128 v[214:217], v156 offset:20480
	ds_read_b128 v[218:221], v156 offset:21504
	ds_read_b128 v[222:225], v156 offset:22528
	ds_read_b128 v[226:229], v156 offset:23552
	global_load_lds_dwordx4 v[146:147], off
	s_add_i32 m0, s74, 0x2000
	s_add_u32 s74, s78, 0x200000
	v_lshl_add_u64 v[148:149], s[78:79], 0, v[130:131]
	s_addc_u32 s75, s79, 0
	s_add_i32 s82, s83, s7
	global_load_lds_dwordx4 v[148:149], off
	v_lshl_add_u64 v[152:153], s[74:75], 0, v[134:135]
	s_mov_b32 m0, s82
	v_lshl_add_u64 v[178:179], s[80:81], 0, v[132:133]
	global_load_lds_dwordx4 v[152:153], off
	v_lshl_add_u64 v[152:153], s[74:75], 0, v[130:131]
	s_add_i32 m0, s82, 0x2000
	s_nop 0
	global_load_lds_dwordx4 v[152:153], off
	v_lshl_add_u64 v[152:153], s[80:81], 0, v[136:137]
	s_mov_b32 m0, s14
	s_nop 0
	global_load_lds_dwordx4 v[152:153], off
	s_mov_b32 m0, s15
	s_nop 0
	global_load_lds_dwordx4 v[178:179], off
	s_waitcnt vmcnt(8)
	s_waitcnt lgkmcnt(0)
	s_setprio 1
	s_barrier
; #define PG8_STAGE(bufoff, gbase, voff) do { _Pragma("unroll") for (int _i = 0; _i < 2; ++_i) \
;         __builtin_amdgcn_global_load_lds((const unsigned*)((const char*)(gbase) + (voff)[_i]), (PG8_LAS unsigned*)(lds + (bufoff) + ldsw + _i * 8192), 16, 0, 0); } while (0)
; #define PG8_LDA(dst, b, h) do { _Pragma("unroll") for (int m = 0; m < 4; ++m) _Pragma("unroll") for (int k = 0; k < 2; ++k) dst[m][k] = *(const PG8_LAS bf16x8*)(lds + PG8_SA(b, h) + aoff + m * 2048 + k * 1024); } while (0)
; #define PG8_LDB(dst, b, h) do { _Pragma("unroll") for (int n = 0; n < 2; ++n) _Pragma("unroll") for (int k = 0; k < 2; ++k) dst[n][k] = *(const PG8_LAS bf16x8*)(lds + PG8_SB(b, h) + boff + n * 2048 + k * 1024); } while (0)
; #define PG8_MMA(ai, bj, At, Bt) do { __builtin_amdgcn_s_setprio(1); _Pragma("unroll") for (int m = 0; m < 4; ++m) _Pragma("unroll") for (int n = 0; n < 2; ++n) _Pragma("unroll") for (int k = 0; k < 2; ++k) \
;         acc[ai][bj][m][n] = __builtin_amdgcn_mfma_f32_16x16x32_bf16(Bt[n][k], At[m][k], acc[ai][bj][m][n], 0, 0, 0); __builtin_amdgcn_s_setprio(0); } while (0)
; template <class Epi, class Sched, bool ALIGN_EPI = false, bool SP2 = false>
; __device__ __forceinline__ void gemm_phase(PG8_LAS unsigned char* lds, const Gemm g, const Sched& S, const Epi& E, const int wv) {
;     ...
;             if constexpr (SP2) {
;             PG8_LDB(B0, 0, 0); PG8_LDB(B1, 0, 1); PG8_SCHED; PG8_LDA(At, 0, 0); PG8_STAGE(PG8_SA(1, 1), a1 + hstep, voffA);
;             PG8_WAIT_V(8); PG8_WAIT_L(0); PG8_BAR; PG8_MMA(0, 0, At, B0); PG8_MMA(0, 1, At, B1); PG8_BAR; PG8_SCHED;
;             PG8_LDA(At, 0, 1); PG8_STAGE(PG8_SB(0, 0), b2, voffB); PG8_STAGE(PG8_SB(0, 1), b2 + hstep, voffB); PG8_STAGE(PG8_SA(0, 0), a2, voffA);
;             PG8_WAIT_V(8); PG8_WAIT_L(0); PG8_BAR; PG8_MMA(1, 0, At, B0); PG8_MMA(1, 1, At, B1); PG8_BAR; PG8_SCHED;
;             PG8_LDB(B0, 1, 0); PG8_LDB(B1, 1, 1); PG8_SCHED; PG8_LDA(At, 1, 0); PG8_STAGE(PG8_SA(0, 1), a2 + hstep, voffA);
;             PG8_WAIT_V(8); PG8_WAIT_L(0); PG8_BAR; PG8_MMA(0, 0, At, B0); PG8_MMA(0, 1, At, B1); PG8_BAR; PG8_SCHED;
;             PG8_LDA(At, 1, 1); PG8_STAGE(PG8_SB(1, 0), b3, voffB); PG8_STAGE(PG8_SB(1, 1), b3 + hstep, voffB); PG8_STAGE(PG8_SA(1, 0), a3, voffA);
;             PG8_WAIT_V(8); PG8_WAIT_L(0); PG8_BAR; PG8_MMA(1, 0, At, B0); PG8_MMA(1, 1, At, B1); PG8_BAR; PG8_SCHED;
	v_mfma_f32_16x16x32_bf16 v[62:65], v[142:145], v[198:201], v[62:65]
	v_mfma_f32_16x16x32_bf16 v[58:61], v[162:165], v[198:201], v[58:61]
	v_mfma_f32_16x16x32_bf16 v[46:49], v[142:145], v[206:209], v[46:49]
	v_mfma_f32_16x16x32_bf16 v[42:45], v[162:165], v[206:209], v[42:45]
	v_mfma_f32_16x16x32_bf16 v[30:33], v[142:145], v[214:217], v[30:33]
	v_mfma_f32_16x16x32_bf16 v[26:29], v[162:165], v[214:217], v[26:29]
	v_mfma_f32_16x16x32_bf16 v[14:17], v[142:145], v[222:225], v[14:17]
	v_mfma_f32_16x16x32_bf16 v[10:13], v[162:165], v[222:225], v[10:13]
	v_mfma_f32_16x16x32_bf16 v[62:65], v[158:161], v[202:205], v[62:65]
	v_mfma_f32_16x16x32_bf16 v[58:61], v[166:169], v[202:205], v[58:61]
	v_mfma_f32_16x16x32_bf16 v[46:49], v[158:161], v[210:213], v[46:49]
	v_mfma_f32_16x16x32_bf16 v[42:45], v[166:169], v[210:213], v[42:45]
	v_mfma_f32_16x16x32_bf16 v[30:33], v[158:161], v[218:221], v[30:33]
	v_mfma_f32_16x16x32_bf16 v[26:29], v[166:169], v[218:221], v[26:29]
	v_mfma_f32_16x16x32_bf16 v[14:17], v[158:161], v[226:229], v[14:17]
	v_mfma_f32_16x16x32_bf16 v[10:13], v[166:169], v[226:229], v[10:13]
	v_mfma_f32_16x16x32_bf16 v[54:57], v[170:173], v[198:201], v[54:57]
	v_mfma_f32_16x16x32_bf16 v[50:53], v[190:193], v[198:201], v[50:53]
	v_mfma_f32_16x16x32_bf16 v[38:41], v[170:173], v[206:209], v[38:41]
	v_mfma_f32_16x16x32_bf16 v[34:37], v[190:193], v[206:209], v[34:37]
	v_mfma_f32_16x16x32_bf16 v[22:25], v[170:173], v[214:217], v[22:25]
	v_mfma_f32_16x16x32_bf16 v[18:21], v[190:193], v[214:217], v[18:21]
	v_mfma_f32_16x16x32_bf16 v[6:9], v[170:173], v[222:225], v[6:9]
	v_mfma_f32_16x16x32_bf16 v[2:5], v[190:193], v[222:225], v[2:5]
	v_mfma_f32_16x16x32_bf16 v[54:57], v[174:177], v[202:205], v[54:57]
	v_mfma_f32_16x16x32_bf16 v[50:53], v[194:197], v[202:205], v[50:53]
	v_mfma_f32_16x16x32_bf16 v[38:41], v[174:177], v[210:213], v[38:41]
	v_mfma_f32_16x16x32_bf16 v[34:37], v[194:197], v[210:213], v[34:37]
	v_mfma_f32_16x16x32_bf16 v[22:25], v[174:177], v[218:221], v[22:25]
	v_mfma_f32_16x16x32_bf16 v[18:21], v[194:197], v[218:221], v[18:21]
	v_mfma_f32_16x16x32_bf16 v[6:9], v[174:177], v[226:229], v[6:9]
	v_mfma_f32_16x16x32_bf16 v[2:5], v[194:197], v[226:229], v[2:5]
	s_barrier
	s_setprio 0
	s_add_i32 s82, 0, 0x18000
	v_add_u32_e32 v157, s82, v154
	s_add_i32 s83, 0, 0x1c000
	ds_read_b128 v[142:145], v157
	ds_read_b128 v[158:161], v157 offset:1024
	ds_read_b128 v[162:165], v157 offset:2048
	ds_read_b128 v[166:169], v157 offset:3072
	v_add_u32_e32 v157, s83, v154
	ds_read_b128 v[170:173], v157
	ds_read_b128 v[174:177], v157 offset:1024
	ds_read_b128 v[190:193], v157 offset:2048
	ds_read_b128 v[194:197], v157 offset:3072
	s_add_u32 s74, s80, 0x200000
	s_addc_u32 s75, s81, 0
	s_mov_b32 m0, s16
	v_lshl_add_u64 v[230:231], s[74:75], 0, v[136:137]
	ds_read_b128 v[198:201], v156 offset:32768
	ds_read_b128 v[202:205], v156 offset:33792
	ds_read_b128 v[206:209], v156 offset:34816
	ds_read_b128 v[210:213], v156 offset:35840
	ds_read_b128 v[214:217], v156 offset:36864
	ds_read_b128 v[218:221], v156 offset:37888
	ds_read_b128 v[222:225], v156 offset:38912
	ds_read_b128 v[226:229], v156 offset:39936
	global_load_lds_dwordx4 v[230:231], off
	v_lshl_add_u64 v[230:231], s[74:75], 0, v[132:133]
	s_mov_b32 m0, s17
	s_nop 0
	global_load_lds_dwordx4 v[230:231], off
	s_waitcnt vmcnt(8)
	s_waitcnt lgkmcnt(0)
	s_setprio 1
	s_barrier
	v_mfma_f32_16x16x32_bf16 v[126:129], v[142:145], v[198:201], v[126:129]
	v_mfma_f32_16x16x32_bf16 v[122:125], v[162:165], v[198:201], v[122:125]
	v_mfma_f32_16x16x32_bf16 v[110:113], v[142:145], v[206:209], v[110:113]
	v_mfma_f32_16x16x32_bf16 v[106:109], v[162:165], v[206:209], v[106:109]
	v_mfma_f32_16x16x32_bf16 v[94:97], v[142:145], v[214:217], v[94:97]
	v_mfma_f32_16x16x32_bf16 v[90:93], v[162:165], v[214:217], v[90:93]
	v_mfma_f32_16x16x32_bf16 v[78:81], v[142:145], v[222:225], v[78:81]
	v_mfma_f32_16x16x32_bf16 v[74:77], v[162:165], v[222:225], v[74:77]
	v_mfma_f32_16x16x32_bf16 v[126:129], v[158:161], v[202:205], v[126:129]
	v_mfma_f32_16x16x32_bf16 v[122:125], v[166:169], v[202:205], v[122:125]
	v_mfma_f32_16x16x32_bf16 v[110:113], v[158:161], v[210:213], v[110:113]
	v_mfma_f32_16x16x32_bf16 v[106:109], v[166:169], v[210:213], v[106:109]
	v_mfma_f32_16x16x32_bf16 v[94:97], v[158:161], v[218:221], v[94:97]
	v_mfma_f32_16x16x32_bf16 v[90:93], v[166:169], v[218:221], v[90:93]
	v_mfma_f32_16x16x32_bf16 v[78:81], v[158:161], v[226:229], v[78:81]
	v_mfma_f32_16x16x32_bf16 v[74:77], v[166:169], v[226:229], v[74:77]
	v_mfma_f32_16x16x32_bf16 v[118:121], v[170:173], v[198:201], v[118:121]
	v_mfma_f32_16x16x32_bf16 v[114:117], v[190:193], v[198:201], v[114:117]
	v_mfma_f32_16x16x32_bf16 v[102:105], v[170:173], v[206:209], v[102:105]
	v_mfma_f32_16x16x32_bf16 v[98:101], v[190:193], v[206:209], v[98:101]
	v_mfma_f32_16x16x32_bf16 v[86:89], v[170:173], v[214:217], v[86:89]
	v_mfma_f32_16x16x32_bf16 v[82:85], v[190:193], v[214:217], v[82:85]
	v_mfma_f32_16x16x32_bf16 v[70:73], v[170:173], v[222:225], v[70:73]
	v_mfma_f32_16x16x32_bf16 v[66:69], v[190:193], v[222:225], v[66:69]
	v_mfma_f32_16x16x32_bf16 v[118:121], v[174:177], v[202:205], v[118:121]
	v_mfma_f32_16x16x32_bf16 v[114:117], v[194:197], v[202:205], v[114:117]
	v_mfma_f32_16x16x32_bf16 v[102:105], v[174:177], v[210:213], v[102:105]
	v_mfma_f32_16x16x32_bf16 v[98:101], v[194:197], v[210:213], v[98:101]
	v_mfma_f32_16x16x32_bf16 v[86:89], v[174:177], v[218:221], v[86:89]
	v_mfma_f32_16x16x32_bf16 v[82:85], v[194:197], v[218:221], v[82:85]
	v_mfma_f32_16x16x32_bf16 v[70:73], v[174:177], v[226:229], v[70:73]
	v_mfma_f32_16x16x32_bf16 v[66:69], v[194:197], v[226:229], v[66:69]
	s_barrier
; #define PG8_STAGE(bufoff, gbase, voff) do { _Pragma("unroll") for (int _i = 0; _i < 2; ++_i) \
;         __builtin_amdgcn_global_load_lds((const unsigned*)((const char*)(gbase) + (voff)[_i]), (PG8_LAS unsigned*)(lds + (bufoff) + ldsw + _i * 8192), 16, 0, 0); } while (0)
; #define PG8_LDA(dst, b, h) do { _Pragma("unroll") for (int m = 0; m < 4; ++m) _Pragma("unroll") for (int k = 0; k < 2; ++k) dst[m][k] = *(const PG8_LAS bf16x8*)(lds + PG8_SA(b, h) + aoff + m * 2048 + k * 1024); } while (0)
; #define PG8_LDB(dst, b, h) do { _Pragma("unroll") for (int n = 0; n < 2; ++n) _Pragma("unroll") for (int k = 0; k < 2; ++k) dst[n][k] = *(const PG8_LAS bf16x8*)(lds + PG8_SB(b, h) + boff + n * 2048 + k * 1024); } while (0)
; #define PG8_MMA(ai, bj, At, Bt) do { __builtin_amdgcn_s_setprio(1); _Pragma("unroll") for (int m = 0; m < 4; ++m) _Pragma("unroll") for (int n = 0; n < 2; ++n) _Pragma("unroll") for (int k = 0; k < 2; ++k) \
;         acc[ai][bj][m][n] = __builtin_amdgcn_mfma_f32_16x16x32_bf16(Bt[n][k], At[m][k], acc[ai][bj][m][n], 0, 0, 0); __builtin_amdgcn_s_setprio(0); } while (0)
; template <class Epi, class Sched, bool ALIGN_EPI = false, bool SP2 = false>
; __device__ __forceinline__ void gemm_phase(PG8_LAS unsigned char* lds, const Gemm g, const Sched& S, const Epi& E, const int wv) {
;     ...
;             if constexpr (SP2) {
;             PG8_LDB(B0, 0, 0); PG8_LDB(B1, 0, 1); PG8_SCHED; PG8_LDA(At, 0, 0); PG8_STAGE(PG8_SA(1, 1), a1 + hstep, voffA);
;             PG8_WAIT_V(8); PG8_WAIT_L(0); PG8_BAR; PG8_MMA(0, 0, At, B0); PG8_MMA(0, 1, At, B1); PG8_BAR; PG8_SCHED;
;             PG8_LDA(At, 0, 1); PG8_STAGE(PG8_SB(0, 0), b2, voffB); PG8_STAGE(PG8_SB(0, 1), b2 + hstep, voffB); PG8_STAGE(PG8_SA(0, 0), a2, voffA);
;             PG8_WAIT_V(8); PG8_WAIT_L(0); PG8_BAR; PG8_MMA(1, 0, At, B0); PG8_MMA(1, 1, At, B1); PG8_BAR; PG8_SCHED;
;             PG8_LDB(B0, 1, 0); PG8_LDB(B1, 1, 1); PG8_SCHED; PG8_LDA(At, 1, 0); PG8_STAGE(PG8_SA(0, 1), a2 + hstep, voffA);
;             PG8_WAIT_V(8); PG8_WAIT_L(0); PG8_BAR; PG8_MMA(0, 0, At, B0); PG8_MMA(0, 1, At, B1); PG8_BAR; PG8_SCHED;
;             PG8_LDA(At, 1, 1); PG8_STAGE(PG8_SB(1, 0), b3, voffB); PG8_STAGE(PG8_SB(1, 1), b3 + hstep, voffB); PG8_STAGE(PG8_SA(1, 0), a3, voffA);
;             PG8_WAIT_V(8); PG8_WAIT_L(0); PG8_BAR; PG8_MMA(1, 0, At, B0); PG8_MMA(1, 1, At, B1); PG8_BAR; PG8_SCHED;
	s_setprio 0
	s_add_i32 s74, s82, s7
	v_lshl_add_u64 v[146:147], v[146:147], 0, s[26:27]
	s_mov_b32 m0, s74
	ds_read_b128 v[198:201], v156 offset:49152
	ds_read_b128 v[202:205], v156 offset:50176
	ds_read_b128 v[206:209], v156 offset:51200
	ds_read_b128 v[210:213], v156 offset:52224
	ds_read_b128 v[214:217], v156 offset:53248
	ds_read_b128 v[218:221], v156 offset:54272
	ds_read_b128 v[222:225], v156 offset:55296
	ds_read_b128 v[226:229], v156 offset:56320
	global_load_lds_dwordx4 v[146:147], off
	s_add_i32 m0, s74, 0x2000
	s_add_u32 s74, s78, 0x200080
	v_lshl_add_u64 v[146:147], v[148:149], 0, s[26:27]
	s_addc_u32 s75, s79, 0
	s_add_i32 s78, s83, s7
	global_load_lds_dwordx4 v[146:147], off
	v_lshl_add_u64 v[146:147], s[74:75], 0, v[134:135]
	s_mov_b32 m0, s78
	s_nop 0
	global_load_lds_dwordx4 v[146:147], off
	v_lshl_add_u64 v[146:147], s[74:75], 0, v[130:131]
	s_add_i32 m0, s78, 0x2000
	s_nop 0
	global_load_lds_dwordx4 v[146:147], off
	v_lshl_add_u64 v[146:147], v[152:153], 0, s[26:27]
	s_mov_b32 m0, s22
	s_nop 0
	global_load_lds_dwordx4 v[146:147], off
	v_lshl_add_u64 v[146:147], v[178:179], 0, s[26:27]
	s_mov_b32 m0, s23
	s_nop 0
	global_load_lds_dwordx4 v[146:147], off
	s_waitcnt vmcnt(8)
	s_waitcnt lgkmcnt(0)
	s_setprio 1
	s_barrier
	v_mfma_f32_16x16x32_bf16 v[62:65], v[142:145], v[198:201], v[62:65]
	v_mfma_f32_16x16x32_bf16 v[58:61], v[162:165], v[198:201], v[58:61]
	v_mfma_f32_16x16x32_bf16 v[46:49], v[142:145], v[206:209], v[46:49]
	v_mfma_f32_16x16x32_bf16 v[42:45], v[162:165], v[206:209], v[42:45]
	v_mfma_f32_16x16x32_bf16 v[30:33], v[142:145], v[214:217], v[30:33]
	v_mfma_f32_16x16x32_bf16 v[26:29], v[162:165], v[214:217], v[26:29]
	v_mfma_f32_16x16x32_bf16 v[14:17], v[142:145], v[222:225], v[14:17]
	v_mfma_f32_16x16x32_bf16 v[10:13], v[162:165], v[222:225], v[10:13]
	v_mfma_f32_16x16x32_bf16 v[62:65], v[158:161], v[202:205], v[62:65]
	v_mfma_f32_16x16x32_bf16 v[58:61], v[166:169], v[202:205], v[58:61]
	v_mfma_f32_16x16x32_bf16 v[46:49], v[158:161], v[210:213], v[46:49]
	v_mfma_f32_16x16x32_bf16 v[42:45], v[166:169], v[210:213], v[42:45]
	v_mfma_f32_16x16x32_bf16 v[30:33], v[158:161], v[218:221], v[30:33]
	v_mfma_f32_16x16x32_bf16 v[26:29], v[166:169], v[218:221], v[26:29]
	v_mfma_f32_16x16x32_bf16 v[14:17], v[158:161], v[226:229], v[14:17]
	v_mfma_f32_16x16x32_bf16 v[10:13], v[166:169], v[226:229], v[10:13]
	v_mfma_f32_16x16x32_bf16 v[54:57], v[170:173], v[198:201], v[54:57]
	v_mfma_f32_16x16x32_bf16 v[50:53], v[190:193], v[198:201], v[50:53]
	v_mfma_f32_16x16x32_bf16 v[38:41], v[170:173], v[206:209], v[38:41]
	v_mfma_f32_16x16x32_bf16 v[34:37], v[190:193], v[206:209], v[34:37]
	v_mfma_f32_16x16x32_bf16 v[22:25], v[170:173], v[214:217], v[22:25]
	v_mfma_f32_16x16x32_bf16 v[18:21], v[190:193], v[214:217], v[18:21]
	v_mfma_f32_16x16x32_bf16 v[6:9], v[170:173], v[222:225], v[6:9]
	v_mfma_f32_16x16x32_bf16 v[2:5], v[190:193], v[222:225], v[2:5]
	v_mfma_f32_16x16x32_bf16 v[54:57], v[174:177], v[202:205], v[54:57]
	v_mfma_f32_16x16x32_bf16 v[50:53], v[194:197], v[202:205], v[50:53]
	v_mfma_f32_16x16x32_bf16 v[38:41], v[174:177], v[210:213], v[38:41]
	v_mfma_f32_16x16x32_bf16 v[34:37], v[194:197], v[210:213], v[34:37]
	v_mfma_f32_16x16x32_bf16 v[22:25], v[174:177], v[218:221], v[22:25]
	v_mfma_f32_16x16x32_bf16 v[18:21], v[194:197], v[218:221], v[18:21]
	v_mfma_f32_16x16x32_bf16 v[6:9], v[174:177], v[226:229], v[6:9]
	v_mfma_f32_16x16x32_bf16 v[2:5], v[194:197], v[226:229], v[2:5]
	s_barrier
	s_setprio 0
	s_add_i32 s66, s66, 2
	s_add_u32 s61, s61, 0x100
	s_addc_u32 s62, s62, 0
	s_add_u32 s76, s76, 0x100
	s_addc_u32 s77, s77, 0
	s_cmpk_gt_u32 s66, 0x7d
	s_cbranch_scc0 .LBB0_40
	s_and_b64 vcc, exec, s[8:9]
	s_cbranch_vccz .LBB0_43
	s_barrier

; #define PG8_STAGE(bufoff, gbase, voff) do { _Pragma("unroll") for (int _i = 0; _i < 2; ++_i) \
;         __builtin_amdgcn_global_load_lds((const unsigned*)((const char*)(gbase) + (voff)[_i]), (PG8_LAS unsigned*)(lds + (bufoff) + ldsw + _i * 8192), 16, 0, 0); } while (0)
; #define PG8_LDA(dst, b, h) do { _Pragma("unroll") for (int m = 0; m < 4; ++m) _Pragma("unroll") for (int k = 0; k < 2; ++k) dst[m][k] = *(const PG8_LAS bf16x8*)(lds + PG8_SA(b, h) + aoff + m * 2048 + k * 1024); } while (0)
; #define PG8_LDB(dst, b, h) do { _Pragma("unroll") for (int n = 0; n < 2; ++n) _Pragma("unroll") for (int k = 0; k < 2; ++k) dst[n][k] = *(const PG8_LAS bf16x8*)(lds + PG8_SB(b, h) + boff + n * 2048 + k * 1024); } while (0)
; #define PG8_MMA(ai, bj, At, Bt) do { __builtin_amdgcn_s_setprio(1); _Pragma("unroll") for (int m = 0; m < 4; ++m) _Pragma("unroll") for (int n = 0; n < 2; ++n) _Pragma("unroll") for (int k = 0; k < 2; ++k) \
;         acc[ai][bj][m][n] = __builtin_amdgcn_mfma_f32_16x16x32_bf16(Bt[n][k], At[m][k], acc[ai][bj][m][n], 0, 0, 0); __builtin_amdgcn_s_setprio(0); } while (0)
; #define PG8_WAIT_V(n) asm volatile("s_waitcnt vmcnt(" #n ")" ::: "memory")
; #define PG8_WAIT_L(n) asm volatile("s_waitcnt lgkmcnt(" #n ")" ::: "memory")
; #define PG8_BAR __builtin_amdgcn_s_barrier()
; #define PG8_SCHED __builtin_amdgcn_sched_barrier(0)
; template <class Epi, class Sched, bool ALIGN_EPI = false, bool SP2 = false>
; __device__ __forceinline__ void gemm_phase(PG8_LAS unsigned char* lds, const Gemm g, const Sched& S, const Epi& E, const int wv) {
;     ...
;             PG8_LDB(B0, 0, 0); PG8_LDB(B1, 0, 1); PG8_SCHED; PG8_LDA(At, 0, 0); PG8_STAGE(PG8_SA(1, 1), a1 + hstep, voffA);
;             PG8_WAIT_V(8); PG8_WAIT_L(0); PG8_BAR; PG8_MMA(0, 0, At, B0); PG8_MMA(0, 1, At, B1); PG8_BAR; PG8_SCHED;
;             PG8_LDA(At, 0, 1); PG8_STAGE(PG8_SB(0, 0), b2, voffB); PG8_STAGE(PG8_SB(0, 1), b2 + hstep, voffB); PG8_STAGE(PG8_SA(0, 0), a2, voffA);
;             PG8_WAIT_V(8); PG8_WAIT_L(0); PG8_BAR; PG8_MMA(1, 0, At, B0); PG8_MMA(1, 1, At, B1); PG8_BAR; PG8_SCHED;
.LBB0_60:
	s_add_u32 s62, s48, s34
	s_addc_u32 s66, s49, 0
	s_add_u32 s35, s62, 0x100
	s_addc_u32 s71, s66, 0
	s_and_b64 s[74:75], s[84:85], exec
	s_cselect_b32 s89, s1, s71
	s_cselect_b32 s88, s0, s35
	s_add_u32 s34, s46, s34
	s_addc_u32 s35, s47, 0
	s_add_u32 s71, s34, 0x100
	s_addc_u32 s74, s35, 0
	s_add_i32 s77, 0, 0x10000
	s_and_b64 s[34:35], s[84:85], exec
	s_cselect_b32 s91, s81, s74
	s_cselect_b32 s90, s80, s71
	s_add_i32 s71, 0, 0x14000
	s_add_u32 s74, s62, 0x200080
	s_addc_u32 s75, s66, 0
	s_add_i32 s66, s77, s7
	s_add_i32 m0, s14, 0xc000
	s_add_i32 s62, s14, 0xe000
	s_add_i32 s79, s66, 0x2000
	s_add_u32 vcc_lo, s90, 0x200000
	v_add_u32_e32 v90, s77, v0
	v_add_u32_e32 v106, s71, v0
	s_addc_u32 vcc_hi, s91, 0
	s_add_i32 s97, s71, s7
	ds_read_b128 v[78:81], v90
	ds_read_b128 v[82:85], v90 offset:1024
	ds_read_b128 v[86:89], v90 offset:2048
	ds_read_b128 v[90:93], v90 offset:3072
	ds_read_b128 v[94:97], v106
	s_waitcnt lgkmcnt(0)
	ds_read_b128 v[98:101], v106 offset:1024
	ds_read_b128 v[102:105], v106 offset:2048
	ds_read_b128 v[106:109], v106 offset:3072
	s_add_i32 s40, s97, 0x2000
	s_add_i32 s35, 0, 0x18000
	s_add_i32 s43, 0, 0x1c000
	s_add_u32 s86, s88, 0x200000
	s_addc_u32 s87, s89, 0
	s_add_i32 s34, s35, s7
	s_add_i32 s42, s34, 0x2000
	s_add_u32 s84, s90, 0x200080
	s_addc_u32 s85, s91, 0
	s_add_i32 s71, s43, s7
	s_add_i32 s77, s71, 0x2000
	v_lshl_add_u64 v[142:143], s[74:75], 0, v[72:73]
	ds_read_b128 v[110:113], v77
	ds_read_b128 v[114:117], v77 offset:1024
	ds_read_b128 v[118:121], v77 offset:2048
	ds_read_b128 v[122:125], v77 offset:3072
	ds_read_b128 v[126:129], v77 offset:4096
	ds_read_b128 v[130:133], v77 offset:5120
	ds_read_b128 v[134:137], v77 offset:6144
	ds_read_b128 v[138:141], v77 offset:7168
	global_load_lds_dwordx4 v[142:143], off
	v_lshl_add_u64 v[142:143], s[74:75], 0, v[68:69]
	s_mov_b32 m0, s62
	s_nop 0
	global_load_lds_dwordx4 v[142:143], off
	s_waitcnt vmcnt(8)
	s_waitcnt lgkmcnt(0)
	s_setprio 1
	s_barrier
	v_mfma_f32_16x16x32_bf16 v[62:65], v[78:81], v[110:113], v[62:65]
	v_mfma_f32_16x16x32_bf16 v[58:61], v[86:89], v[110:113], v[58:61]
	v_mfma_f32_16x16x32_bf16 v[54:57], v[78:81], v[118:121], v[54:57]
	v_mfma_f32_16x16x32_bf16 v[50:53], v[86:89], v[118:121], v[50:53]
	v_mfma_f32_16x16x32_bf16 v[38:41], v[78:81], v[126:129], v[38:41]
	v_mfma_f32_16x16x32_bf16 v[34:37], v[86:89], v[126:129], v[34:37]
	v_mfma_f32_16x16x32_bf16 v[22:25], v[78:81], v[134:137], v[22:25]
	v_mfma_f32_16x16x32_bf16 v[18:21], v[86:89], v[134:137], v[18:21]
	v_mfma_f32_16x16x32_bf16 v[62:65], v[82:85], v[114:117], v[62:65]
	v_mfma_f32_16x16x32_bf16 v[58:61], v[90:93], v[114:117], v[58:61]
	v_mfma_f32_16x16x32_bf16 v[54:57], v[82:85], v[122:125], v[54:57]
	v_mfma_f32_16x16x32_bf16 v[50:53], v[90:93], v[122:125], v[50:53]
	v_mfma_f32_16x16x32_bf16 v[38:41], v[82:85], v[130:133], v[38:41]
	v_mfma_f32_16x16x32_bf16 v[34:37], v[90:93], v[130:133], v[34:37]
	v_mfma_f32_16x16x32_bf16 v[22:25], v[82:85], v[138:141], v[22:25]
	v_mfma_f32_16x16x32_bf16 v[18:21], v[90:93], v[138:141], v[18:21]
	v_mfma_f32_16x16x32_bf16 v[46:49], v[94:97], v[110:113], v[46:49]
	v_mfma_f32_16x16x32_bf16 v[42:45], v[102:105], v[110:113], v[42:45]
	v_mfma_f32_16x16x32_bf16 v[30:33], v[94:97], v[118:121], v[30:33]
	v_mfma_f32_16x16x32_bf16 v[26:29], v[102:105], v[118:121], v[26:29]
	v_mfma_f32_16x16x32_bf16 v[14:17], v[94:97], v[126:129], v[14:17]
	v_mfma_f32_16x16x32_bf16 v[10:13], v[102:105], v[126:129], v[10:13]
	v_mfma_f32_16x16x32_bf16 v[6:9], v[94:97], v[134:137], v[6:9]
	v_mfma_f32_16x16x32_bf16 v[2:5], v[102:105], v[134:137], v[2:5]
	v_mfma_f32_16x16x32_bf16 v[46:49], v[98:101], v[114:117], v[46:49]
	v_mfma_f32_16x16x32_bf16 v[42:45], v[106:109], v[114:117], v[42:45]
	v_mfma_f32_16x16x32_bf16 v[30:33], v[98:101], v[122:125], v[30:33]
	v_mfma_f32_16x16x32_bf16 v[26:29], v[106:109], v[122:125], v[26:29]
	v_mfma_f32_16x16x32_bf16 v[14:17], v[98:101], v[130:133], v[14:17]
	v_mfma_f32_16x16x32_bf16 v[10:13], v[106:109], v[130:133], v[10:13]
	v_mfma_f32_16x16x32_bf16 v[6:9], v[98:101], v[138:141], v[6:9]
	v_mfma_f32_16x16x32_bf16 v[2:5], v[106:109], v[138:141], v[2:5]
	s_barrier
	s_setprio 0
	s_mov_b32 m0, s66
	v_lshl_add_u64 v[142:143], s[90:91], 0, v[70:71]
	global_load_lds_dwordx4 v[142:143], off
	v_lshl_add_u64 v[144:145], s[90:91], 0, v[66:67]
	s_mov_b32 m0, s79
	v_lshl_add_u64 v[78:79], vcc, 0, v[70:71]
	global_load_lds_dwordx4 v[144:145], off
	s_mov_b32 m0, s97
	v_lshl_add_u64 v[146:147], s[88:89], 0, v[72:73]
	global_load_lds_dwordx4 v[78:79], off
	v_lshl_add_u64 v[78:79], vcc, 0, v[66:67]
	s_mov_b32 m0, s40
	v_lshl_add_u64 v[148:149], s[88:89], 0, v[68:69]
	global_load_lds_dwordx4 v[78:79], off
	s_mov_b32 m0, s14
	s_nop 0
	global_load_lds_dwordx4 v[146:147], off
	s_mov_b32 m0, s17
	s_nop 0
	global_load_lds_dwordx4 v[148:149], off
	s_waitcnt vmcnt(8)
	s_waitcnt lgkmcnt(0)
	s_barrier
; #define PG8_STAGE(bufoff, gbase, voff) do { _Pragma("unroll") for (int _i = 0; _i < 2; ++_i) \
;         __builtin_amdgcn_global_load_lds((const unsigned*)((const char*)(gbase) + (voff)[_i]), (PG8_LAS unsigned*)(lds + (bufoff) + ldsw + _i * 8192), 16, 0, 0); } while (0)
; #define PG8_LDA(dst, b, h) do { _Pragma("unroll") for (int m = 0; m < 4; ++m) _Pragma("unroll") for (int k = 0; k < 2; ++k) dst[m][k] = *(const PG8_LAS bf16x8*)(lds + PG8_SA(b, h) + aoff + m * 2048 + k * 1024); } while (0)
; #define PG8_LDB(dst, b, h) do { _Pragma("unroll") for (int n = 0; n < 2; ++n) _Pragma("unroll") for (int k = 0; k < 2; ++k) dst[n][k] = *(const PG8_LAS bf16x8*)(lds + PG8_SB(b, h) + boff + n * 2048 + k * 1024); } while (0)
; #define PG8_MMA(ai, bj, At, Bt) do { __builtin_amdgcn_s_setprio(1); _Pragma("unroll") for (int m = 0; m < 4; ++m) _Pragma("unroll") for (int n = 0; n < 2; ++n) _Pragma("unroll") for (int k = 0; k < 2; ++k) \
;         acc[ai][bj][m][n] = __builtin_amdgcn_mfma_f32_16x16x32_bf16(Bt[n][k], At[m][k], acc[ai][bj][m][n], 0, 0, 0); __builtin_amdgcn_s_setprio(0); } while (0)
; #define PG8_WAIT_V(n) asm volatile("s_waitcnt vmcnt(" #n ")" ::: "memory")
; #define PG8_WAIT_L(n) asm volatile("s_waitcnt lgkmcnt(" #n ")" ::: "memory")
; #define PG8_BAR __builtin_amdgcn_s_barrier()
; #define PG8_SCHED __builtin_amdgcn_sched_barrier(0)
; template <class Epi, class Sched, bool ALIGN_EPI = false, bool SP2 = false>
; __device__ __forceinline__ void gemm_phase(PG8_LAS unsigned char* lds, const Gemm g, const Sched& S, const Epi& E, const int wv) {
;     ...
;             PG8_WAIT_V(8); PG8_WAIT_L(0); PG8_BAR; PG8_MMA(1, 0, At, B0); PG8_MMA(1, 1, At, B1); PG8_BAR; PG8_SCHED;
;             PG8_LDB(B0, 1, 0); PG8_LDB(B1, 1, 1); PG8_SCHED; PG8_LDA(At, 1, 0); PG8_STAGE(PG8_SA(0, 1), a2 + hstep, voffA);
;             PG8_WAIT_V(8); PG8_WAIT_L(0); PG8_BAR; PG8_MMA(0, 0, At, B0); PG8_MMA(0, 1, At, B1); PG8_BAR; PG8_SCHED;
;             PG8_LDA(At, 1, 1); PG8_STAGE(PG8_SB(1, 0), b3, voffB); PG8_STAGE(PG8_SB(1, 1), b3 + hstep, voffB); PG8_STAGE(PG8_SA(1, 0), a3, voffA);
;             PG8_WAIT_V(8); PG8_WAIT_L(0); PG8_BAR; PG8_MMA(1, 0, At, B0); PG8_MMA(1, 1, At, B1); PG8_BAR; PG8_SCHED;
	s_setprio 1
	s_setprio 0
	s_setprio 1
	s_setprio 0
	s_barrier
	v_add_u32_e32 v90, s35, v0
	v_add_u32_e32 v106, s43, v0
	ds_read_b128 v[78:81], v90
	ds_read_b128 v[82:85], v90 offset:1024
	ds_read_b128 v[86:89], v90 offset:2048
	ds_read_b128 v[90:93], v90 offset:3072
	ds_read_b128 v[94:97], v106
	ds_read_b128 v[98:101], v106 offset:1024
	ds_read_b128 v[102:105], v106 offset:2048
	ds_read_b128 v[106:109], v106 offset:3072
	s_mov_b32 m0, s22
	v_lshl_add_u64 v[152:153], s[86:87], 0, v[72:73]
	ds_read_b128 v[110:113], v77 offset:32768
	ds_read_b128 v[114:117], v77 offset:33792
	ds_read_b128 v[118:121], v77 offset:34816
	ds_read_b128 v[122:125], v77 offset:35840
	ds_read_b128 v[126:129], v77 offset:36864
	ds_read_b128 v[130:133], v77 offset:37888
	ds_read_b128 v[134:137], v77 offset:38912
	ds_read_b128 v[138:141], v77 offset:39936
	global_load_lds_dwordx4 v[152:153], off
	v_lshl_add_u64 v[152:153], s[86:87], 0, v[68:69]
	s_mov_b32 m0, s23
	s_nop 0
	global_load_lds_dwordx4 v[152:153], off
	s_waitcnt vmcnt(8)
	s_waitcnt lgkmcnt(0)
	s_setprio 1
	s_barrier
	v_mfma_f32_16x16x32_bf16 v[62:65], v[78:81], v[110:113], v[62:65]
	v_mfma_f32_16x16x32_bf16 v[58:61], v[86:89], v[110:113], v[58:61]
	v_mfma_f32_16x16x32_bf16 v[54:57], v[78:81], v[118:121], v[54:57]
	v_mfma_f32_16x16x32_bf16 v[50:53], v[86:89], v[118:121], v[50:53]
	v_mfma_f32_16x16x32_bf16 v[38:41], v[78:81], v[126:129], v[38:41]
	v_mfma_f32_16x16x32_bf16 v[34:37], v[86:89], v[126:129], v[34:37]
	v_mfma_f32_16x16x32_bf16 v[22:25], v[78:81], v[134:137], v[22:25]
	v_mfma_f32_16x16x32_bf16 v[18:21], v[86:89], v[134:137], v[18:21]
	v_mfma_f32_16x16x32_bf16 v[62:65], v[82:85], v[114:117], v[62:65]
	v_mfma_f32_16x16x32_bf16 v[58:61], v[90:93], v[114:117], v[58:61]
	v_mfma_f32_16x16x32_bf16 v[54:57], v[82:85], v[122:125], v[54:57]
	v_mfma_f32_16x16x32_bf16 v[50:53], v[90:93], v[122:125], v[50:53]
	v_mfma_f32_16x16x32_bf16 v[38:41], v[82:85], v[130:133], v[38:41]
	v_mfma_f32_16x16x32_bf16 v[34:37], v[90:93], v[130:133], v[34:37]
	v_mfma_f32_16x16x32_bf16 v[22:25], v[82:85], v[138:141], v[22:25]
	v_mfma_f32_16x16x32_bf16 v[18:21], v[90:93], v[138:141], v[18:21]
	v_mfma_f32_16x16x32_bf16 v[46:49], v[94:97], v[110:113], v[46:49]
	v_mfma_f32_16x16x32_bf16 v[42:45], v[102:105], v[110:113], v[42:45]
	v_mfma_f32_16x16x32_bf16 v[30:33], v[94:97], v[118:121], v[30:33]
	v_mfma_f32_16x16x32_bf16 v[26:29], v[102:105], v[118:121], v[26:29]
	v_mfma_f32_16x16x32_bf16 v[14:17], v[94:97], v[126:129], v[14:17]
	v_mfma_f32_16x16x32_bf16 v[10:13], v[102:105], v[126:129], v[10:13]
	v_mfma_f32_16x16x32_bf16 v[6:9], v[94:97], v[134:137], v[6:9]
	v_mfma_f32_16x16x32_bf16 v[2:5], v[102:105], v[134:137], v[2:5]
	v_mfma_f32_16x16x32_bf16 v[46:49], v[98:101], v[114:117], v[46:49]
	v_mfma_f32_16x16x32_bf16 v[42:45], v[106:109], v[114:117], v[42:45]
	v_mfma_f32_16x16x32_bf16 v[30:33], v[98:101], v[122:125], v[30:33]
	v_mfma_f32_16x16x32_bf16 v[26:29], v[106:109], v[122:125], v[26:29]
	v_mfma_f32_16x16x32_bf16 v[14:17], v[98:101], v[130:133], v[14:17]
	v_mfma_f32_16x16x32_bf16 v[10:13], v[106:109], v[130:133], v[10:13]
	v_mfma_f32_16x16x32_bf16 v[6:9], v[98:101], v[138:141], v[6:9]
	v_mfma_f32_16x16x32_bf16 v[2:5], v[106:109], v[138:141], v[2:5]
	s_barrier
	s_setprio 0
	s_mov_b32 m0, s34
	v_lshl_add_u64 v[78:79], v[142:143], 0, s[26:27]
	global_load_lds_dwordx4 v[78:79], off
	v_lshl_add_u64 v[78:79], v[144:145], 0, s[26:27]
	s_mov_b32 m0, s42
	s_nop 0
	global_load_lds_dwordx4 v[78:79], off
	v_lshl_add_u64 v[78:79], s[84:85], 0, v[70:71]
	s_mov_b32 m0, s71
	s_nop 0
	global_load_lds_dwordx4 v[78:79], off
	v_lshl_add_u64 v[78:79], s[84:85], 0, v[66:67]
	s_mov_b32 m0, s77
	s_nop 0
	global_load_lds_dwordx4 v[78:79], off
	v_lshl_add_u64 v[78:79], v[146:147], 0, s[26:27]
	s_mov_b32 m0, s41
	s_nop 0
	global_load_lds_dwordx4 v[78:79], off
	v_lshl_add_u64 v[78:79], v[148:149], 0, s[26:27]
	s_mov_b32 m0, s57
	s_nop 0
	global_load_lds_dwordx4 v[78:79], off
	s_waitcnt vmcnt(8)
	s_waitcnt lgkmcnt(0)
	s_barrier
	s_setprio 1
	s_setprio 0
	s_setprio 1
	s_setprio 0
	s_barrier
	s_movk_i32 s34, 0x100
	s_andn2_b64 vcc, exec, s[82:83]
	s_mov_b64 s[84:85], -1
	s_mov_b64 s[82:83], 0
	s_cbranch_vccz .LBB0_60
	s_and_b64 vcc, exec, s[68:69]
	s_cbranch_vccz .LBB0_63
	s_barrier

; #define PG8_STAGE(bufoff, gbase, voff) do { _Pragma("unroll") for (int _i = 0; _i < 2; ++_i) \
;         __builtin_amdgcn_global_load_lds((const unsigned*)((const char*)(gbase) + (voff)[_i]), (PG8_LAS unsigned*)(lds + (bufoff) + ldsw + _i * 8192), 16, 0, 0); } while (0)
; #define PG8_LDA(dst, b, h) do { _Pragma("unroll") for (int m = 0; m < 4; ++m) _Pragma("unroll") for (int k = 0; k < 2; ++k) dst[m][k] = *(const PG8_LAS bf16x8*)(lds + PG8_SA(b, h) + aoff + m * 2048 + k * 1024); } while (0)
; #define PG8_LDB(dst, b, h) do { _Pragma("unroll") for (int n = 0; n < 2; ++n) _Pragma("unroll") for (int k = 0; k < 2; ++k) dst[n][k] = *(const PG8_LAS bf16x8*)(lds + PG8_SB(b, h) + boff + n * 2048 + k * 1024); } while (0)
; #define PG8_MMA(ai, bj, At, Bt) do { __builtin_amdgcn_s_setprio(1); _Pragma("unroll") for (int m = 0; m < 4; ++m) _Pragma("unroll") for (int n = 0; n < 2; ++n) _Pragma("unroll") for (int k = 0; k < 2; ++k) \
;         acc[ai][bj][m][n] = __builtin_amdgcn_mfma_f32_16x16x32_bf16(Bt[n][k], At[m][k], acc[ai][bj][m][n], 0, 0, 0); __builtin_amdgcn_s_setprio(0); } while (0)
; #define PG8_WAIT_V(n) asm volatile("s_waitcnt vmcnt(" #n ")" ::: "memory")
; #define PG8_WAIT_L(n) asm volatile("s_waitcnt lgkmcnt(" #n ")" ::: "memory")
; #define PG8_BAR __builtin_amdgcn_s_barrier()
; #define PG8_SCHED __builtin_amdgcn_sched_barrier(0)
; template <class Epi, class Sched, bool ALIGN_EPI = false, bool SP2 = false>
; __device__ __forceinline__ void gemm_phase(PG8_LAS unsigned char* lds, const Gemm g, const Sched& S, const Epi& E, const int wv) {
;     ...
;             PG8_LDB(B0, 0, 0); PG8_LDB(B1, 0, 1); PG8_SCHED; PG8_LDA(At, 0, 0); PG8_STAGE(PG8_SA(1, 1), a1 + hstep, voffA);
;             PG8_WAIT_V(8); PG8_WAIT_L(0); PG8_BAR; PG8_MMA(0, 0, At, B0); PG8_MMA(0, 1, At, B1); PG8_BAR; PG8_SCHED;
;             PG8_LDA(At, 0, 1); PG8_STAGE(PG8_SB(0, 0), b2, voffB); PG8_STAGE(PG8_SB(0, 1), b2 + hstep, voffB); PG8_STAGE(PG8_SA(0, 0), a2, voffA);
;             PG8_WAIT_V(8); PG8_WAIT_L(0); PG8_BAR; PG8_MMA(1, 0, At, B0); PG8_MMA(1, 1, At, B1); PG8_BAR; PG8_SCHED;
.LBB0_78:
	s_add_u32 s74, s76, 0xfff80080
	s_addc_u32 s75, s77, -1
	s_add_i32 s82, 0, 0x10000
	s_cmp_eq_u32 s66, 28
	s_cselect_b32 s81, s34, s75
	s_cselect_b32 s80, s35, s74
	v_add_u32_e32 v145, s82, v142
	s_cselect_b32 s79, s47, s62
	s_cselect_b32 s78, s49, s61
	s_add_i32 s83, 0, 0x14000
	ds_read_b128 v[152:155], v145
	ds_read_b128 v[156:159], v145 offset:1024
	ds_read_b128 v[160:163], v145 offset:2048
	ds_read_b128 v[164:167], v145 offset:3072
	v_add_u32_e32 v145, s83, v142
	ds_read_b128 v[168:171], v145
	ds_read_b128 v[172:175], v145 offset:1024
	ds_read_b128 v[176:179], v145 offset:2048
	ds_read_b128 v[190:193], v145 offset:3072
	v_lshl_add_u64 v[146:147], s[76:77], 0, v[140:141]
	s_add_i32 m0, s14, 0xc000
	ds_read_b128 v[194:197], v144
	ds_read_b128 v[198:201], v144 offset:1024
	ds_read_b128 v[202:205], v144 offset:2048
	ds_read_b128 v[206:209], v144 offset:3072
	ds_read_b128 v[210:213], v144 offset:4096
	ds_read_b128 v[214:217], v144 offset:5120
	ds_read_b128 v[218:221], v144 offset:6144
	ds_read_b128 v[222:225], v144 offset:7168
	global_load_lds_dwordx4 v[146:147], off
	v_lshl_add_u64 v[146:147], s[76:77], 0, v[138:139]
	s_add_i32 m0, s14, 0xe000
	s_nop 0
	global_load_lds_dwordx4 v[146:147], off
	s_waitcnt vmcnt(8)
	s_waitcnt lgkmcnt(0)
	s_setprio 1
	s_barrier
	v_mfma_f32_16x16x32_bf16 v[126:129], v[152:155], v[194:197], v[126:129]
	v_mfma_f32_16x16x32_bf16 v[122:125], v[160:163], v[194:197], v[122:125]
	v_mfma_f32_16x16x32_bf16 v[110:113], v[152:155], v[202:205], v[110:113]
	v_mfma_f32_16x16x32_bf16 v[106:109], v[160:163], v[202:205], v[106:109]
	v_mfma_f32_16x16x32_bf16 v[94:97], v[152:155], v[210:213], v[94:97]
	v_mfma_f32_16x16x32_bf16 v[90:93], v[160:163], v[210:213], v[90:93]
	v_mfma_f32_16x16x32_bf16 v[78:81], v[152:155], v[218:221], v[78:81]
	v_mfma_f32_16x16x32_bf16 v[74:77], v[160:163], v[218:221], v[74:77]
	v_mfma_f32_16x16x32_bf16 v[126:129], v[156:159], v[198:201], v[126:129]
	v_mfma_f32_16x16x32_bf16 v[122:125], v[164:167], v[198:201], v[122:125]
	v_mfma_f32_16x16x32_bf16 v[110:113], v[156:159], v[206:209], v[110:113]
	v_mfma_f32_16x16x32_bf16 v[106:109], v[164:167], v[206:209], v[106:109]
	v_mfma_f32_16x16x32_bf16 v[94:97], v[156:159], v[214:217], v[94:97]
	v_mfma_f32_16x16x32_bf16 v[90:93], v[164:167], v[214:217], v[90:93]
	v_mfma_f32_16x16x32_bf16 v[78:81], v[156:159], v[222:225], v[78:81]
	v_mfma_f32_16x16x32_bf16 v[74:77], v[164:167], v[222:225], v[74:77]
	v_mfma_f32_16x16x32_bf16 v[118:121], v[168:171], v[194:197], v[118:121]
	v_mfma_f32_16x16x32_bf16 v[114:117], v[176:179], v[194:197], v[114:117]
	v_mfma_f32_16x16x32_bf16 v[102:105], v[168:171], v[202:205], v[102:105]
	v_mfma_f32_16x16x32_bf16 v[98:101], v[176:179], v[202:205], v[98:101]
	v_mfma_f32_16x16x32_bf16 v[86:89], v[168:171], v[210:213], v[86:89]
	v_mfma_f32_16x16x32_bf16 v[82:85], v[176:179], v[210:213], v[82:85]
	v_mfma_f32_16x16x32_bf16 v[70:73], v[168:171], v[218:221], v[70:73]
	v_mfma_f32_16x16x32_bf16 v[66:69], v[176:179], v[218:221], v[66:69]
	v_mfma_f32_16x16x32_bf16 v[118:121], v[172:175], v[198:201], v[118:121]
	v_mfma_f32_16x16x32_bf16 v[114:117], v[190:193], v[198:201], v[114:117]
	v_mfma_f32_16x16x32_bf16 v[102:105], v[172:175], v[206:209], v[102:105]
	v_mfma_f32_16x16x32_bf16 v[98:101], v[190:193], v[206:209], v[98:101]
	v_mfma_f32_16x16x32_bf16 v[86:89], v[172:175], v[214:217], v[86:89]
	v_mfma_f32_16x16x32_bf16 v[82:85], v[190:193], v[214:217], v[82:85]
	v_mfma_f32_16x16x32_bf16 v[70:73], v[172:175], v[222:225], v[70:73]
	v_mfma_f32_16x16x32_bf16 v[66:69], v[190:193], v[222:225], v[66:69]
	s_barrier
	s_setprio 0
	s_add_i32 s74, s82, s7
	v_lshl_add_u64 v[146:147], s[78:79], 0, v[134:135]
	s_mov_b32 m0, s74
	ds_read_b128 v[194:197], v144 offset:16384
	ds_read_b128 v[198:201], v144 offset:17408
	ds_read_b128 v[202:205], v144 offset:18432
	ds_read_b128 v[206:209], v144 offset:19456
	ds_read_b128 v[210:213], v144 offset:20480
	ds_read_b128 v[214:217], v144 offset:21504
	ds_read_b128 v[218:221], v144 offset:22528
	ds_read_b128 v[222:225], v144 offset:23552
	global_load_lds_dwordx4 v[146:147], off
	s_add_i32 m0, s74, 0x2000
	s_add_u32 s74, s78, 0x80000
	v_lshl_add_u64 v[148:149], s[78:79], 0, v[130:131]
	s_addc_u32 s75, s79, 0
	s_add_i32 s82, s83, s7
	global_load_lds_dwordx4 v[148:149], off
	v_lshl_add_u64 v[226:227], s[74:75], 0, v[134:135]
	s_mov_b32 m0, s82
	v_lshl_add_u64 v[228:229], s[80:81], 0, v[132:133]
	global_load_lds_dwordx4 v[226:227], off
	v_lshl_add_u64 v[226:227], s[74:75], 0, v[130:131]
	s_add_i32 m0, s82, 0x2000
	s_nop 0
	global_load_lds_dwordx4 v[226:227], off
	v_lshl_add_u64 v[226:227], s[80:81], 0, v[136:137]
	s_mov_b32 m0, s14
	s_nop 0
	global_load_lds_dwordx4 v[226:227], off
	s_mov_b32 m0, s15
	s_nop 0
	global_load_lds_dwordx4 v[228:229], off
	s_waitcnt vmcnt(8)
	s_waitcnt lgkmcnt(0)
	s_setprio 1
	s_barrier
; #define PG8_STAGE(bufoff, gbase, voff) do { _Pragma("unroll") for (int _i = 0; _i < 2; ++_i) \
;         __builtin_amdgcn_global_load_lds((const unsigned*)((const char*)(gbase) + (voff)[_i]), (PG8_LAS unsigned*)(lds + (bufoff) + ldsw + _i * 8192), 16, 0, 0); } while (0)
; #define PG8_LDA(dst, b, h) do { _Pragma("unroll") for (int m = 0; m < 4; ++m) _Pragma("unroll") for (int k = 0; k < 2; ++k) dst[m][k] = *(const PG8_LAS bf16x8*)(lds + PG8_SA(b, h) + aoff + m * 2048 + k * 1024); } while (0)
; #define PG8_LDB(dst, b, h) do { _Pragma("unroll") for (int n = 0; n < 2; ++n) _Pragma("unroll") for (int k = 0; k < 2; ++k) dst[n][k] = *(const PG8_LAS bf16x8*)(lds + PG8_SB(b, h) + boff + n * 2048 + k * 1024); } while (0)
; #define PG8_MMA(ai, bj, At, Bt) do { __builtin_amdgcn_s_setprio(1); _Pragma("unroll") for (int m = 0; m < 4; ++m) _Pragma("unroll") for (int n = 0; n < 2; ++n) _Pragma("unroll") for (int k = 0; k < 2; ++k) \
;         acc[ai][bj][m][n] = __builtin_amdgcn_mfma_f32_16x16x32_bf16(Bt[n][k], At[m][k], acc[ai][bj][m][n], 0, 0, 0); __builtin_amdgcn_s_setprio(0); } while (0)
; #define PG8_WAIT_V(n) asm volatile("s_waitcnt vmcnt(" #n ")" ::: "memory")
; #define PG8_WAIT_L(n) asm volatile("s_waitcnt lgkmcnt(" #n ")" ::: "memory")
; #define PG8_BAR __builtin_amdgcn_s_barrier()
; #define PG8_SCHED __builtin_amdgcn_sched_barrier(0)
; template <class Epi, class Sched, bool ALIGN_EPI = false, bool SP2 = false>
; __device__ __forceinline__ void gemm_phase(PG8_LAS unsigned char* lds, const Gemm g, const Sched& S, const Epi& E, const int wv) {
;     ...
;             PG8_WAIT_V(8); PG8_WAIT_L(0); PG8_BAR; PG8_MMA(1, 0, At, B0); PG8_MMA(1, 1, At, B1); PG8_BAR; PG8_SCHED;
;             PG8_LDB(B0, 1, 0); PG8_LDB(B1, 1, 1); PG8_SCHED; PG8_LDA(At, 1, 0); PG8_STAGE(PG8_SA(0, 1), a2 + hstep, voffA);
;             PG8_WAIT_V(8); PG8_WAIT_L(0); PG8_BAR; PG8_MMA(0, 0, At, B0); PG8_MMA(0, 1, At, B1); PG8_BAR; PG8_SCHED;
	v_mfma_f32_16x16x32_bf16 v[62:65], v[152:155], v[194:197], v[62:65]
	v_mfma_f32_16x16x32_bf16 v[58:61], v[160:163], v[194:197], v[58:61]
	v_mfma_f32_16x16x32_bf16 v[46:49], v[152:155], v[202:205], v[46:49]
	v_mfma_f32_16x16x32_bf16 v[42:45], v[160:163], v[202:205], v[42:45]
	v_mfma_f32_16x16x32_bf16 v[30:33], v[152:155], v[210:213], v[30:33]
	v_mfma_f32_16x16x32_bf16 v[26:29], v[160:163], v[210:213], v[26:29]
	v_mfma_f32_16x16x32_bf16 v[14:17], v[152:155], v[218:221], v[14:17]
	v_mfma_f32_16x16x32_bf16 v[10:13], v[160:163], v[218:221], v[10:13]
	v_mfma_f32_16x16x32_bf16 v[62:65], v[156:159], v[198:201], v[62:65]
	v_mfma_f32_16x16x32_bf16 v[58:61], v[164:167], v[198:201], v[58:61]
	v_mfma_f32_16x16x32_bf16 v[46:49], v[156:159], v[206:209], v[46:49]
	v_mfma_f32_16x16x32_bf16 v[42:45], v[164:167], v[206:209], v[42:45]
	v_mfma_f32_16x16x32_bf16 v[30:33], v[156:159], v[214:217], v[30:33]
	v_mfma_f32_16x16x32_bf16 v[26:29], v[164:167], v[214:217], v[26:29]
	v_mfma_f32_16x16x32_bf16 v[14:17], v[156:159], v[222:225], v[14:17]
	v_mfma_f32_16x16x32_bf16 v[10:13], v[164:167], v[222:225], v[10:13]
	v_mfma_f32_16x16x32_bf16 v[54:57], v[168:171], v[194:197], v[54:57]
	v_mfma_f32_16x16x32_bf16 v[50:53], v[176:179], v[194:197], v[50:53]
	v_mfma_f32_16x16x32_bf16 v[38:41], v[168:171], v[202:205], v[38:41]
	v_mfma_f32_16x16x32_bf16 v[34:37], v[176:179], v[202:205], v[34:37]
	v_mfma_f32_16x16x32_bf16 v[22:25], v[168:171], v[210:213], v[22:25]
	v_mfma_f32_16x16x32_bf16 v[18:21], v[176:179], v[210:213], v[18:21]
	v_mfma_f32_16x16x32_bf16 v[6:9], v[168:171], v[218:221], v[6:9]
	v_mfma_f32_16x16x32_bf16 v[2:5], v[176:179], v[218:221], v[2:5]
	v_mfma_f32_16x16x32_bf16 v[54:57], v[172:175], v[198:201], v[54:57]
	v_mfma_f32_16x16x32_bf16 v[50:53], v[190:193], v[198:201], v[50:53]
	v_mfma_f32_16x16x32_bf16 v[38:41], v[172:175], v[206:209], v[38:41]
	v_mfma_f32_16x16x32_bf16 v[34:37], v[190:193], v[206:209], v[34:37]
	v_mfma_f32_16x16x32_bf16 v[22:25], v[172:175], v[214:217], v[22:25]
	v_mfma_f32_16x16x32_bf16 v[18:21], v[190:193], v[214:217], v[18:21]
	v_mfma_f32_16x16x32_bf16 v[6:9], v[172:175], v[222:225], v[6:9]
	v_mfma_f32_16x16x32_bf16 v[2:5], v[190:193], v[222:225], v[2:5]
	s_barrier
	s_setprio 0
	s_add_i32 s82, 0, 0x18000
	v_add_u32_e32 v145, s82, v142
	s_add_i32 s83, 0, 0x1c000
	ds_read_b128 v[152:155], v145
	ds_read_b128 v[156:159], v145 offset:1024
	ds_read_b128 v[160:163], v145 offset:2048
	ds_read_b128 v[164:167], v145 offset:3072
	v_add_u32_e32 v145, s83, v142
	ds_read_b128 v[168:171], v145
	ds_read_b128 v[172:175], v145 offset:1024
	ds_read_b128 v[176:179], v145 offset:2048
	ds_read_b128 v[190:193], v145 offset:3072
	s_add_u32 s74, s80, 0x80000
	s_addc_u32 s75, s81, 0
	s_mov_b32 m0, s16
	v_lshl_add_u64 v[230:231], s[74:75], 0, v[136:137]
	ds_read_b128 v[194:197], v144 offset:32768
	ds_read_b128 v[198:201], v144 offset:33792
	ds_read_b128 v[202:205], v144 offset:34816
	ds_read_b128 v[206:209], v144 offset:35840
	ds_read_b128 v[210:213], v144 offset:36864
	ds_read_b128 v[214:217], v144 offset:37888
	ds_read_b128 v[218:221], v144 offset:38912
	ds_read_b128 v[222:225], v144 offset:39936
	global_load_lds_dwordx4 v[230:231], off
	v_lshl_add_u64 v[230:231], s[74:75], 0, v[132:133]
	s_mov_b32 m0, s17
	s_nop 0
	global_load_lds_dwordx4 v[230:231], off
	s_waitcnt vmcnt(8)
	s_waitcnt lgkmcnt(0)
	s_setprio 1
	s_barrier
	v_mfma_f32_16x16x32_bf16 v[126:129], v[152:155], v[194:197], v[126:129]
	v_mfma_f32_16x16x32_bf16 v[122:125], v[160:163], v[194:197], v[122:125]
	v_mfma_f32_16x16x32_bf16 v[110:113], v[152:155], v[202:205], v[110:113]
	v_mfma_f32_16x16x32_bf16 v[106:109], v[160:163], v[202:205], v[106:109]
	v_mfma_f32_16x16x32_bf16 v[94:97], v[152:155], v[210:213], v[94:97]
	v_mfma_f32_16x16x32_bf16 v[90:93], v[160:163], v[210:213], v[90:93]
	v_mfma_f32_16x16x32_bf16 v[78:81], v[152:155], v[218:221], v[78:81]
	v_mfma_f32_16x16x32_bf16 v[74:77], v[160:163], v[218:221], v[74:77]
	v_mfma_f32_16x16x32_bf16 v[126:129], v[156:159], v[198:201], v[126:129]
	v_mfma_f32_16x16x32_bf16 v[122:125], v[164:167], v[198:201], v[122:125]
	v_mfma_f32_16x16x32_bf16 v[110:113], v[156:159], v[206:209], v[110:113]
	v_mfma_f32_16x16x32_bf16 v[106:109], v[164:167], v[206:209], v[106:109]
	v_mfma_f32_16x16x32_bf16 v[94:97], v[156:159], v[214:217], v[94:97]
	v_mfma_f32_16x16x32_bf16 v[90:93], v[164:167], v[214:217], v[90:93]
	v_mfma_f32_16x16x32_bf16 v[78:81], v[156:159], v[222:225], v[78:81]
	v_mfma_f32_16x16x32_bf16 v[74:77], v[164:167], v[222:225], v[74:77]
	v_mfma_f32_16x16x32_bf16 v[118:121], v[168:171], v[194:197], v[118:121]
	v_mfma_f32_16x16x32_bf16 v[114:117], v[176:179], v[194:197], v[114:117]
	v_mfma_f32_16x16x32_bf16 v[102:105], v[168:171], v[202:205], v[102:105]
	v_mfma_f32_16x16x32_bf16 v[98:101], v[176:179], v[202:205], v[98:101]
	v_mfma_f32_16x16x32_bf16 v[86:89], v[168:171], v[210:213], v[86:89]
	v_mfma_f32_16x16x32_bf16 v[82:85], v[176:179], v[210:213], v[82:85]
	v_mfma_f32_16x16x32_bf16 v[70:73], v[168:171], v[218:221], v[70:73]
	v_mfma_f32_16x16x32_bf16 v[66:69], v[176:179], v[218:221], v[66:69]
	v_mfma_f32_16x16x32_bf16 v[118:121], v[172:175], v[198:201], v[118:121]
	v_mfma_f32_16x16x32_bf16 v[114:117], v[190:193], v[198:201], v[114:117]
	v_mfma_f32_16x16x32_bf16 v[102:105], v[172:175], v[206:209], v[102:105]
	v_mfma_f32_16x16x32_bf16 v[98:101], v[190:193], v[206:209], v[98:101]
	v_mfma_f32_16x16x32_bf16 v[86:89], v[172:175], v[214:217], v[86:89]
	v_mfma_f32_16x16x32_bf16 v[82:85], v[190:193], v[214:217], v[82:85]
	v_mfma_f32_16x16x32_bf16 v[70:73], v[172:175], v[222:225], v[70:73]
	v_mfma_f32_16x16x32_bf16 v[66:69], v[190:193], v[222:225], v[66:69]
	s_barrier
; #define PG8_STAGE(bufoff, gbase, voff) do { _Pragma("unroll") for (int _i = 0; _i < 2; ++_i) \
;         __builtin_amdgcn_global_load_lds((const unsigned*)((const char*)(gbase) + (voff)[_i]), (PG8_LAS unsigned*)(lds + (bufoff) + ldsw + _i * 8192), 16, 0, 0); } while (0)
; #define PG8_LDA(dst, b, h) do { _Pragma("unroll") for (int m = 0; m < 4; ++m) _Pragma("unroll") for (int k = 0; k < 2; ++k) dst[m][k] = *(const PG8_LAS bf16x8*)(lds + PG8_SA(b, h) + aoff + m * 2048 + k * 1024); } while (0)
; #define PG8_MMA(ai, bj, At, Bt) do { __builtin_amdgcn_s_setprio(1); _Pragma("unroll") for (int m = 0; m < 4; ++m) _Pragma("unroll") for (int n = 0; n < 2; ++n) _Pragma("unroll") for (int k = 0; k < 2; ++k) \
;         acc[ai][bj][m][n] = __builtin_amdgcn_mfma_f32_16x16x32_bf16(Bt[n][k], At[m][k], acc[ai][bj][m][n], 0, 0, 0); __builtin_amdgcn_s_setprio(0); } while (0)
; #define PG8_WAIT_V(n) asm volatile("s_waitcnt vmcnt(" #n ")" ::: "memory")
; #define PG8_WAIT_L(n) asm volatile("s_waitcnt lgkmcnt(" #n ")" ::: "memory")
; #define PG8_BAR __builtin_amdgcn_s_barrier()
; #define PG8_SCHED __builtin_amdgcn_sched_barrier(0)
; template <class Epi, class Sched, bool ALIGN_EPI = false, bool SP2 = false>
; __device__ __forceinline__ void gemm_phase(PG8_LAS unsigned char* lds, const Gemm g, const Sched& S, const Epi& E, const int wv) {
;     ...
;             PG8_LDA(At, 1, 1); PG8_STAGE(PG8_SB(1, 0), b3, voffB); PG8_STAGE(PG8_SB(1, 1), b3 + hstep, voffB); PG8_STAGE(PG8_SA(1, 0), a3, voffA);
;             PG8_WAIT_V(8); PG8_WAIT_L(0); PG8_BAR; PG8_MMA(1, 0, At, B0); PG8_MMA(1, 1, At, B1); PG8_BAR; PG8_SCHED;
	s_setprio 0
	s_add_i32 s74, s82, s7
	v_lshl_add_u64 v[146:147], v[146:147], 0, s[26:27]
	s_mov_b32 m0, s74
	ds_read_b128 v[194:197], v144 offset:49152
	ds_read_b128 v[198:201], v144 offset:50176
	ds_read_b128 v[202:205], v144 offset:51200
	ds_read_b128 v[206:209], v144 offset:52224
	ds_read_b128 v[210:213], v144 offset:53248
	ds_read_b128 v[214:217], v144 offset:54272
	ds_read_b128 v[218:221], v144 offset:55296
	ds_read_b128 v[222:225], v144 offset:56320
	global_load_lds_dwordx4 v[146:147], off
	s_add_i32 m0, s74, 0x2000
	s_add_u32 s74, s78, 0x80080
	v_lshl_add_u64 v[146:147], v[148:149], 0, s[26:27]
	s_addc_u32 s75, s79, 0
	s_add_i32 s78, s83, s7
	global_load_lds_dwordx4 v[146:147], off
	v_lshl_add_u64 v[146:147], s[74:75], 0, v[134:135]
	s_mov_b32 m0, s78
	s_nop 0
	global_load_lds_dwordx4 v[146:147], off
	v_lshl_add_u64 v[146:147], s[74:75], 0, v[130:131]
	s_add_i32 m0, s78, 0x2000
	s_nop 0
	global_load_lds_dwordx4 v[146:147], off
	v_lshl_add_u64 v[146:147], v[226:227], 0, s[26:27]
	s_mov_b32 m0, s22
	s_nop 0
	global_load_lds_dwordx4 v[146:147], off
	v_lshl_add_u64 v[146:147], v[228:229], 0, s[26:27]
	s_mov_b32 m0, s23
	s_nop 0
	global_load_lds_dwordx4 v[146:147], off
	s_waitcnt vmcnt(8)
	s_waitcnt lgkmcnt(0)
	s_setprio 1
	s_barrier
	v_mfma_f32_16x16x32_bf16 v[62:65], v[152:155], v[194:197], v[62:65]
	v_mfma_f32_16x16x32_bf16 v[58:61], v[160:163], v[194:197], v[58:61]
	v_mfma_f32_16x16x32_bf16 v[46:49], v[152:155], v[202:205], v[46:49]
	v_mfma_f32_16x16x32_bf16 v[42:45], v[160:163], v[202:205], v[42:45]
	v_mfma_f32_16x16x32_bf16 v[30:33], v[152:155], v[210:213], v[30:33]
	v_mfma_f32_16x16x32_bf16 v[26:29], v[160:163], v[210:213], v[26:29]
	v_mfma_f32_16x16x32_bf16 v[14:17], v[152:155], v[218:221], v[14:17]
	v_mfma_f32_16x16x32_bf16 v[10:13], v[160:163], v[218:221], v[10:13]
	v_mfma_f32_16x16x32_bf16 v[62:65], v[156:159], v[198:201], v[62:65]
	v_mfma_f32_16x16x32_bf16 v[58:61], v[164:167], v[198:201], v[58:61]
	v_mfma_f32_16x16x32_bf16 v[46:49], v[156:159], v[206:209], v[46:49]
	v_mfma_f32_16x16x32_bf16 v[42:45], v[164:167], v[206:209], v[42:45]
	v_mfma_f32_16x16x32_bf16 v[30:33], v[156:159], v[214:217], v[30:33]
	v_mfma_f32_16x16x32_bf16 v[26:29], v[164:167], v[214:217], v[26:29]
	v_mfma_f32_16x16x32_bf16 v[14:17], v[156:159], v[222:225], v[14:17]
	v_mfma_f32_16x16x32_bf16 v[10:13], v[164:167], v[222:225], v[10:13]
	v_mfma_f32_16x16x32_bf16 v[54:57], v[168:171], v[194:197], v[54:57]
	v_mfma_f32_16x16x32_bf16 v[50:53], v[176:179], v[194:197], v[50:53]
	v_mfma_f32_16x16x32_bf16 v[38:41], v[168:171], v[202:205], v[38:41]
	v_mfma_f32_16x16x32_bf16 v[34:37], v[176:179], v[202:205], v[34:37]
	v_mfma_f32_16x16x32_bf16 v[22:25], v[168:171], v[210:213], v[22:25]
	v_mfma_f32_16x16x32_bf16 v[18:21], v[176:179], v[210:213], v[18:21]
	v_mfma_f32_16x16x32_bf16 v[6:9], v[168:171], v[218:221], v[6:9]
	v_mfma_f32_16x16x32_bf16 v[2:5], v[176:179], v[218:221], v[2:5]
	v_mfma_f32_16x16x32_bf16 v[54:57], v[172:175], v[198:201], v[54:57]
	v_mfma_f32_16x16x32_bf16 v[50:53], v[190:193], v[198:201], v[50:53]
	v_mfma_f32_16x16x32_bf16 v[38:41], v[172:175], v[206:209], v[38:41]
	v_mfma_f32_16x16x32_bf16 v[34:37], v[190:193], v[206:209], v[34:37]
	v_mfma_f32_16x16x32_bf16 v[22:25], v[172:175], v[214:217], v[22:25]
	v_mfma_f32_16x16x32_bf16 v[18:21], v[190:193], v[214:217], v[18:21]
	v_mfma_f32_16x16x32_bf16 v[6:9], v[172:175], v[222:225], v[6:9]
	v_mfma_f32_16x16x32_bf16 v[2:5], v[190:193], v[222:225], v[2:5]
	s_barrier
	s_setprio 0
	s_add_i32 s66, s66, 2
	s_add_u32 s61, s61, 0x100
	s_addc_u32 s62, s62, 0
	s_add_u32 s76, s76, 0x100
	s_addc_u32 s77, s77, 0
	s_cmp_gt_u32 s66, 29
	s_cbranch_scc0 .LBB0_78
	s_and_b64 vcc, exec, s[8:9]
	s_cbranch_vccz .LBB0_81
	s_barrier

; #define PG8_STAGE(bufoff, gbase, voff) do { _Pragma("unroll") for (int _i = 0; _i < 2; ++_i) \
;         __builtin_amdgcn_global_load_lds((const unsigned*)((const char*)(gbase) + (voff)[_i]), (PG8_LAS unsigned*)(lds + (bufoff) + ldsw + _i * 8192), 16, 0, 0); } while (0)
; #define PG8_LDA(dst, b, h) do { _Pragma("unroll") for (int m = 0; m < 4; ++m) _Pragma("unroll") for (int k = 0; k < 2; ++k) dst[m][k] = *(const PG8_LAS bf16x8*)(lds + PG8_SA(b, h) + aoff + m * 2048 + k * 1024); } while (0)
; #define PG8_LDB(dst, b, h) do { _Pragma("unroll") for (int n = 0; n < 2; ++n) _Pragma("unroll") for (int k = 0; k < 2; ++k) dst[n][k] = *(const PG8_LAS bf16x8*)(lds + PG8_SB(b, h) + boff + n * 2048 + k * 1024); } while (0)
; #define PG8_MMA(ai, bj, At, Bt) do { __builtin_amdgcn_s_setprio(1); _Pragma("unroll") for (int m = 0; m < 4; ++m) _Pragma("unroll") for (int n = 0; n < 2; ++n) _Pragma("unroll") for (int k = 0; k < 2; ++k) \
;         acc[ai][bj][m][n] = __builtin_amdgcn_mfma_f32_16x16x32_bf16(Bt[n][k], At[m][k], acc[ai][bj][m][n], 0, 0, 0); __builtin_amdgcn_s_setprio(0); } while (0)
; #define PG8_WAIT_V(n) asm volatile("s_waitcnt vmcnt(" #n ")" ::: "memory")
; #define PG8_WAIT_L(n) asm volatile("s_waitcnt lgkmcnt(" #n ")" ::: "memory")
; #define PG8_BAR __builtin_amdgcn_s_barrier()
; #define PG8_SCHED __builtin_amdgcn_sched_barrier(0)
; template <class Epi, class Sched, bool ALIGN_EPI = false, bool SP2 = false>
; __device__ __forceinline__ void gemm_phase(PG8_LAS unsigned char* lds, const Gemm g, const Sched& S, const Epi& E, const int wv) {
;     ...
;             PG8_LDB(B0, 0, 0); PG8_LDB(B1, 0, 1); PG8_SCHED; PG8_LDA(At, 0, 0); PG8_STAGE(PG8_SA(1, 1), a1 + hstep, voffA);
;             PG8_WAIT_V(8); PG8_WAIT_L(0); PG8_BAR; PG8_MMA(0, 0, At, B0); PG8_MMA(0, 1, At, B1); PG8_BAR; PG8_SCHED;
;             PG8_LDA(At, 0, 1); PG8_STAGE(PG8_SB(0, 0), b2, voffB); PG8_STAGE(PG8_SB(0, 1), b2 + hstep, voffB); PG8_STAGE(PG8_SA(0, 0), a2, voffA);
;             PG8_WAIT_V(8); PG8_WAIT_L(0); PG8_BAR; PG8_MMA(1, 0, At, B0); PG8_MMA(1, 1, At, B1); PG8_BAR; PG8_SCHED;
.LBB0_151:
	s_add_u32 s62, s82, 0xfff80080
	s_addc_u32 s66, s83, -1
	s_add_i32 s68, 0, 0x10000
	s_cmp_eq_u32 s61, 28
	s_cselect_b32 s87, s34, s66
	s_cselect_b32 s86, s35, s62
	v_add_u32_e32 v146, s68, v154
	s_cselect_b32 s85, s47, s58
	s_cselect_b32 s84, s49, s57
	s_add_i32 s62, 0, 0x14000
	ds_read_b128 v[142:145], v146
	ds_read_b128 v[158:161], v146 offset:1024
	ds_read_b128 v[162:165], v146 offset:2048
	ds_read_b128 v[166:169], v146 offset:3072
	v_add_u32_e32 v146, s62, v154
	ds_read_b128 v[170:173], v146
	ds_read_b128 v[174:177], v146 offset:1024
	ds_read_b128 v[190:193], v146 offset:2048
	ds_read_b128 v[194:197], v146 offset:3072
	v_lshl_add_u64 v[146:147], s[82:83], 0, v[140:141]
	s_add_i32 m0, s8, 0xc000
	ds_read_b128 v[198:201], v156
	ds_read_b128 v[202:205], v156 offset:1024
	ds_read_b128 v[206:209], v156 offset:2048
	ds_read_b128 v[210:213], v156 offset:3072
	ds_read_b128 v[214:217], v156 offset:4096
	ds_read_b128 v[218:221], v156 offset:5120
	ds_read_b128 v[222:225], v156 offset:6144
	ds_read_b128 v[226:229], v156 offset:7168
	global_load_lds_dwordx4 v[146:147], off
	v_lshl_add_u64 v[146:147], s[82:83], 0, v[138:139]
	s_add_i32 m0, s8, 0xe000
	s_nop 0
	global_load_lds_dwordx4 v[146:147], off
	s_waitcnt vmcnt(8)
	s_waitcnt lgkmcnt(0)
	s_setprio 1
	s_barrier
	v_mfma_f32_16x16x32_bf16 v[126:129], v[142:145], v[198:201], v[126:129]
	v_mfma_f32_16x16x32_bf16 v[122:125], v[162:165], v[198:201], v[122:125]
	v_mfma_f32_16x16x32_bf16 v[110:113], v[142:145], v[206:209], v[110:113]
	v_mfma_f32_16x16x32_bf16 v[106:109], v[162:165], v[206:209], v[106:109]
	v_mfma_f32_16x16x32_bf16 v[94:97], v[142:145], v[214:217], v[94:97]
	v_mfma_f32_16x16x32_bf16 v[90:93], v[162:165], v[214:217], v[90:93]
	v_mfma_f32_16x16x32_bf16 v[78:81], v[142:145], v[222:225], v[78:81]
	v_mfma_f32_16x16x32_bf16 v[74:77], v[162:165], v[222:225], v[74:77]
	v_mfma_f32_16x16x32_bf16 v[126:129], v[158:161], v[202:205], v[126:129]
	v_mfma_f32_16x16x32_bf16 v[122:125], v[166:169], v[202:205], v[122:125]
	v_mfma_f32_16x16x32_bf16 v[110:113], v[158:161], v[210:213], v[110:113]
	v_mfma_f32_16x16x32_bf16 v[106:109], v[166:169], v[210:213], v[106:109]
	v_mfma_f32_16x16x32_bf16 v[94:97], v[158:161], v[218:221], v[94:97]
	v_mfma_f32_16x16x32_bf16 v[90:93], v[166:169], v[218:221], v[90:93]
	v_mfma_f32_16x16x32_bf16 v[78:81], v[158:161], v[226:229], v[78:81]
	v_mfma_f32_16x16x32_bf16 v[74:77], v[166:169], v[226:229], v[74:77]
	v_mfma_f32_16x16x32_bf16 v[118:121], v[170:173], v[198:201], v[118:121]
	v_mfma_f32_16x16x32_bf16 v[114:117], v[190:193], v[198:201], v[114:117]
	v_mfma_f32_16x16x32_bf16 v[102:105], v[170:173], v[206:209], v[102:105]
	v_mfma_f32_16x16x32_bf16 v[98:101], v[190:193], v[206:209], v[98:101]
	v_mfma_f32_16x16x32_bf16 v[86:89], v[170:173], v[214:217], v[86:89]
	v_mfma_f32_16x16x32_bf16 v[82:85], v[190:193], v[214:217], v[82:85]
	v_mfma_f32_16x16x32_bf16 v[70:73], v[170:173], v[222:225], v[70:73]
	v_mfma_f32_16x16x32_bf16 v[66:69], v[190:193], v[222:225], v[66:69]
	v_mfma_f32_16x16x32_bf16 v[118:121], v[174:177], v[202:205], v[118:121]
	v_mfma_f32_16x16x32_bf16 v[114:117], v[194:197], v[202:205], v[114:117]
	v_mfma_f32_16x16x32_bf16 v[102:105], v[174:177], v[210:213], v[102:105]
	v_mfma_f32_16x16x32_bf16 v[98:101], v[194:197], v[210:213], v[98:101]
	v_mfma_f32_16x16x32_bf16 v[86:89], v[174:177], v[218:221], v[86:89]
	v_mfma_f32_16x16x32_bf16 v[82:85], v[194:197], v[218:221], v[82:85]
	v_mfma_f32_16x16x32_bf16 v[70:73], v[174:177], v[226:229], v[70:73]
	v_mfma_f32_16x16x32_bf16 v[66:69], v[194:197], v[226:229], v[66:69]
	s_barrier
	s_setprio 0
	s_add_i32 s66, s68, s7
	v_lshl_add_u64 v[146:147], s[84:85], 0, v[134:135]
	s_mov_b32 m0, s66
	ds_read_b128 v[198:201], v156 offset:16384
	ds_read_b128 v[202:205], v156 offset:17408
	ds_read_b128 v[206:209], v156 offset:18432
	ds_read_b128 v[210:213], v156 offset:19456
	ds_read_b128 v[214:217], v156 offset:20480
	ds_read_b128 v[218:221], v156 offset:21504
	ds_read_b128 v[222:225], v156 offset:22528
	ds_read_b128 v[226:229], v156 offset:23552
	global_load_lds_dwordx4 v[146:147], off
	s_add_i32 m0, s66, 0x2000
	s_add_u32 s68, s84, 0x80000
	v_lshl_add_u64 v[148:149], s[84:85], 0, v[130:131]
	s_addc_u32 s69, s85, 0
	s_add_i32 s62, s62, s7
	global_load_lds_dwordx4 v[148:149], off
	v_lshl_add_u64 v[152:153], s[68:69], 0, v[134:135]
	s_mov_b32 m0, s62
	v_lshl_add_u64 v[178:179], s[86:87], 0, v[132:133]
	global_load_lds_dwordx4 v[152:153], off
	v_lshl_add_u64 v[152:153], s[68:69], 0, v[130:131]
	s_add_i32 m0, s62, 0x2000
	s_nop 0
	global_load_lds_dwordx4 v[152:153], off
	v_lshl_add_u64 v[152:153], s[86:87], 0, v[136:137]
	s_mov_b32 m0, s8
	s_nop 0
	global_load_lds_dwordx4 v[152:153], off
	s_mov_b32 m0, s9
	s_nop 0
	global_load_lds_dwordx4 v[178:179], off
	s_waitcnt vmcnt(8)
	s_waitcnt lgkmcnt(0)
	s_setprio 1
	s_barrier
; #define PG8_STAGE(bufoff, gbase, voff) do { _Pragma("unroll") for (int _i = 0; _i < 2; ++_i) \
;         __builtin_amdgcn_global_load_lds((const unsigned*)((const char*)(gbase) + (voff)[_i]), (PG8_LAS unsigned*)(lds + (bufoff) + ldsw + _i * 8192), 16, 0, 0); } while (0)
; #define PG8_LDA(dst, b, h) do { _Pragma("unroll") for (int m = 0; m < 4; ++m) _Pragma("unroll") for (int k = 0; k < 2; ++k) dst[m][k] = *(const PG8_LAS bf16x8*)(lds + PG8_SA(b, h) + aoff + m * 2048 + k * 1024); } while (0)
; #define PG8_LDB(dst, b, h) do { _Pragma("unroll") for (int n = 0; n < 2; ++n) _Pragma("unroll") for (int k = 0; k < 2; ++k) dst[n][k] = *(const PG8_LAS bf16x8*)(lds + PG8_SB(b, h) + boff + n * 2048 + k * 1024); } while (0)
; #define PG8_MMA(ai, bj, At, Bt) do { __builtin_amdgcn_s_setprio(1); _Pragma("unroll") for (int m = 0; m < 4; ++m) _Pragma("unroll") for (int n = 0; n < 2; ++n) _Pragma("unroll") for (int k = 0; k < 2; ++k) \
;         acc[ai][bj][m][n] = __builtin_amdgcn_mfma_f32_16x16x32_bf16(Bt[n][k], At[m][k], acc[ai][bj][m][n], 0, 0, 0); __builtin_amdgcn_s_setprio(0); } while (0)
; #define PG8_WAIT_V(n) asm volatile("s_waitcnt vmcnt(" #n ")" ::: "memory")
; #define PG8_WAIT_L(n) asm volatile("s_waitcnt lgkmcnt(" #n ")" ::: "memory")
; #define PG8_BAR __builtin_amdgcn_s_barrier()
; #define PG8_SCHED __builtin_amdgcn_sched_barrier(0)
; template <class Epi, class Sched, bool ALIGN_EPI = false, bool SP2 = false>
; __device__ __forceinline__ void gemm_phase(PG8_LAS unsigned char* lds, const Gemm g, const Sched& S, const Epi& E, const int wv) {
;     ...
;             PG8_WAIT_V(8); PG8_WAIT_L(0); PG8_BAR; PG8_MMA(1, 0, At, B0); PG8_MMA(1, 1, At, B1); PG8_BAR; PG8_SCHED;
;             PG8_LDB(B0, 1, 0); PG8_LDB(B1, 1, 1); PG8_SCHED; PG8_LDA(At, 1, 0); PG8_STAGE(PG8_SA(0, 1), a2 + hstep, voffA);
;             PG8_WAIT_V(8); PG8_WAIT_L(0); PG8_BAR; PG8_MMA(0, 0, At, B0); PG8_MMA(0, 1, At, B1); PG8_BAR; PG8_SCHED;
	v_mfma_f32_16x16x32_bf16 v[62:65], v[142:145], v[198:201], v[62:65]
	v_mfma_f32_16x16x32_bf16 v[58:61], v[162:165], v[198:201], v[58:61]
	v_mfma_f32_16x16x32_bf16 v[46:49], v[142:145], v[206:209], v[46:49]
	v_mfma_f32_16x16x32_bf16 v[42:45], v[162:165], v[206:209], v[42:45]
	v_mfma_f32_16x16x32_bf16 v[30:33], v[142:145], v[214:217], v[30:33]
	v_mfma_f32_16x16x32_bf16 v[26:29], v[162:165], v[214:217], v[26:29]
	v_mfma_f32_16x16x32_bf16 v[14:17], v[142:145], v[222:225], v[14:17]
	v_mfma_f32_16x16x32_bf16 v[10:13], v[162:165], v[222:225], v[10:13]
	v_mfma_f32_16x16x32_bf16 v[62:65], v[158:161], v[202:205], v[62:65]
	v_mfma_f32_16x16x32_bf16 v[58:61], v[166:169], v[202:205], v[58:61]
	v_mfma_f32_16x16x32_bf16 v[46:49], v[158:161], v[210:213], v[46:49]
	v_mfma_f32_16x16x32_bf16 v[42:45], v[166:169], v[210:213], v[42:45]
	v_mfma_f32_16x16x32_bf16 v[30:33], v[158:161], v[218:221], v[30:33]
	v_mfma_f32_16x16x32_bf16 v[26:29], v[166:169], v[218:221], v[26:29]
	v_mfma_f32_16x16x32_bf16 v[14:17], v[158:161], v[226:229], v[14:17]
	v_mfma_f32_16x16x32_bf16 v[10:13], v[166:169], v[226:229], v[10:13]
	v_mfma_f32_16x16x32_bf16 v[54:57], v[170:173], v[198:201], v[54:57]
	v_mfma_f32_16x16x32_bf16 v[50:53], v[190:193], v[198:201], v[50:53]
	v_mfma_f32_16x16x32_bf16 v[38:41], v[170:173], v[206:209], v[38:41]
	v_mfma_f32_16x16x32_bf16 v[34:37], v[190:193], v[206:209], v[34:37]
	v_mfma_f32_16x16x32_bf16 v[22:25], v[170:173], v[214:217], v[22:25]
	v_mfma_f32_16x16x32_bf16 v[18:21], v[190:193], v[214:217], v[18:21]
	v_mfma_f32_16x16x32_bf16 v[6:9], v[170:173], v[222:225], v[6:9]
	v_mfma_f32_16x16x32_bf16 v[2:5], v[190:193], v[222:225], v[2:5]
	v_mfma_f32_16x16x32_bf16 v[54:57], v[174:177], v[202:205], v[54:57]
	v_mfma_f32_16x16x32_bf16 v[50:53], v[194:197], v[202:205], v[50:53]
	v_mfma_f32_16x16x32_bf16 v[38:41], v[174:177], v[210:213], v[38:41]
	v_mfma_f32_16x16x32_bf16 v[34:37], v[194:197], v[210:213], v[34:37]
	v_mfma_f32_16x16x32_bf16 v[22:25], v[174:177], v[218:221], v[22:25]
	v_mfma_f32_16x16x32_bf16 v[18:21], v[194:197], v[218:221], v[18:21]
	v_mfma_f32_16x16x32_bf16 v[6:9], v[174:177], v[226:229], v[6:9]
	v_mfma_f32_16x16x32_bf16 v[2:5], v[194:197], v[226:229], v[2:5]
	s_barrier
	s_setprio 0
	s_add_i32 s62, 0, 0x18000
	v_add_u32_e32 v157, s62, v154
	s_add_i32 s66, 0, 0x1c000
	ds_read_b128 v[142:145], v157
	ds_read_b128 v[158:161], v157 offset:1024
	ds_read_b128 v[162:165], v157 offset:2048
	ds_read_b128 v[166:169], v157 offset:3072
	v_add_u32_e32 v157, s66, v154
	ds_read_b128 v[170:173], v157
	ds_read_b128 v[174:177], v157 offset:1024
	ds_read_b128 v[190:193], v157 offset:2048
	ds_read_b128 v[194:197], v157 offset:3072
	s_add_u32 s68, s86, 0x80000
	s_addc_u32 s69, s87, 0
	s_mov_b32 m0, s14
	v_lshl_add_u64 v[230:231], s[68:69], 0, v[136:137]
	ds_read_b128 v[198:201], v156 offset:32768
	ds_read_b128 v[202:205], v156 offset:33792
	ds_read_b128 v[206:209], v156 offset:34816
	ds_read_b128 v[210:213], v156 offset:35840
	ds_read_b128 v[214:217], v156 offset:36864
	ds_read_b128 v[218:221], v156 offset:37888
	ds_read_b128 v[222:225], v156 offset:38912
	ds_read_b128 v[226:229], v156 offset:39936
	global_load_lds_dwordx4 v[230:231], off
	v_lshl_add_u64 v[230:231], s[68:69], 0, v[132:133]
	s_mov_b32 m0, s15
	s_nop 0
	global_load_lds_dwordx4 v[230:231], off
	s_waitcnt vmcnt(8)
	s_waitcnt lgkmcnt(0)
	s_setprio 1
	s_barrier
	v_mfma_f32_16x16x32_bf16 v[126:129], v[142:145], v[198:201], v[126:129]
	v_mfma_f32_16x16x32_bf16 v[122:125], v[162:165], v[198:201], v[122:125]
	v_mfma_f32_16x16x32_bf16 v[110:113], v[142:145], v[206:209], v[110:113]
	v_mfma_f32_16x16x32_bf16 v[106:109], v[162:165], v[206:209], v[106:109]
	v_mfma_f32_16x16x32_bf16 v[94:97], v[142:145], v[214:217], v[94:97]
	v_mfma_f32_16x16x32_bf16 v[90:93], v[162:165], v[214:217], v[90:93]
	v_mfma_f32_16x16x32_bf16 v[78:81], v[142:145], v[222:225], v[78:81]
	v_mfma_f32_16x16x32_bf16 v[74:77], v[162:165], v[222:225], v[74:77]
	v_mfma_f32_16x16x32_bf16 v[126:129], v[158:161], v[202:205], v[126:129]
	v_mfma_f32_16x16x32_bf16 v[122:125], v[166:169], v[202:205], v[122:125]
	v_mfma_f32_16x16x32_bf16 v[110:113], v[158:161], v[210:213], v[110:113]
	v_mfma_f32_16x16x32_bf16 v[106:109], v[166:169], v[210:213], v[106:109]
	v_mfma_f32_16x16x32_bf16 v[94:97], v[158:161], v[218:221], v[94:97]
	v_mfma_f32_16x16x32_bf16 v[90:93], v[166:169], v[218:221], v[90:93]
	v_mfma_f32_16x16x32_bf16 v[78:81], v[158:161], v[226:229], v[78:81]
	v_mfma_f32_16x16x32_bf16 v[74:77], v[166:169], v[226:229], v[74:77]
	v_mfma_f32_16x16x32_bf16 v[118:121], v[170:173], v[198:201], v[118:121]
	v_mfma_f32_16x16x32_bf16 v[114:117], v[190:193], v[198:201], v[114:117]
	v_mfma_f32_16x16x32_bf16 v[102:105], v[170:173], v[206:209], v[102:105]
	v_mfma_f32_16x16x32_bf16 v[98:101], v[190:193], v[206:209], v[98:101]
	v_mfma_f32_16x16x32_bf16 v[86:89], v[170:173], v[214:217], v[86:89]
	v_mfma_f32_16x16x32_bf16 v[82:85], v[190:193], v[214:217], v[82:85]
	v_mfma_f32_16x16x32_bf16 v[70:73], v[170:173], v[222:225], v[70:73]
	v_mfma_f32_16x16x32_bf16 v[66:69], v[190:193], v[222:225], v[66:69]
	v_mfma_f32_16x16x32_bf16 v[118:121], v[174:177], v[202:205], v[118:121]
	v_mfma_f32_16x16x32_bf16 v[114:117], v[194:197], v[202:205], v[114:117]
	v_mfma_f32_16x16x32_bf16 v[102:105], v[174:177], v[210:213], v[102:105]
	v_mfma_f32_16x16x32_bf16 v[98:101], v[194:197], v[210:213], v[98:101]
	v_mfma_f32_16x16x32_bf16 v[86:89], v[174:177], v[218:221], v[86:89]
	v_mfma_f32_16x16x32_bf16 v[82:85], v[194:197], v[218:221], v[82:85]
	v_mfma_f32_16x16x32_bf16 v[70:73], v[174:177], v[226:229], v[70:73]
	v_mfma_f32_16x16x32_bf16 v[66:69], v[194:197], v[226:229], v[66:69]
	s_barrier
; #define PG8_STAGE(bufoff, gbase, voff) do { _Pragma("unroll") for (int _i = 0; _i < 2; ++_i) \
;         __builtin_amdgcn_global_load_lds((const unsigned*)((const char*)(gbase) + (voff)[_i]), (PG8_LAS unsigned*)(lds + (bufoff) + ldsw + _i * 8192), 16, 0, 0); } while (0)
; #define PG8_LDA(dst, b, h) do { _Pragma("unroll") for (int m = 0; m < 4; ++m) _Pragma("unroll") for (int k = 0; k < 2; ++k) dst[m][k] = *(const PG8_LAS bf16x8*)(lds + PG8_SA(b, h) + aoff + m * 2048 + k * 1024); } while (0)
; #define PG8_MMA(ai, bj, At, Bt) do { __builtin_amdgcn_s_setprio(1); _Pragma("unroll") for (int m = 0; m < 4; ++m) _Pragma("unroll") for (int n = 0; n < 2; ++n) _Pragma("unroll") for (int k = 0; k < 2; ++k) \
;         acc[ai][bj][m][n] = __builtin_amdgcn_mfma_f32_16x16x32_bf16(Bt[n][k], At[m][k], acc[ai][bj][m][n], 0, 0, 0); __builtin_amdgcn_s_setprio(0); } while (0)
; #define PG8_WAIT_V(n) asm volatile("s_waitcnt vmcnt(" #n ")" ::: "memory")
; #define PG8_WAIT_L(n) asm volatile("s_waitcnt lgkmcnt(" #n ")" ::: "memory")
; #define PG8_BAR __builtin_amdgcn_s_barrier()
; #define PG8_SCHED __builtin_amdgcn_sched_barrier(0)
; template <class Epi, class Sched, bool ALIGN_EPI = false, bool SP2 = false>
; __device__ __forceinline__ void gemm_phase(PG8_LAS unsigned char* lds, const Gemm g, const Sched& S, const Epi& E, const int wv) {
;     ...
;             PG8_LDA(At, 1, 1); PG8_STAGE(PG8_SB(1, 0), b3, voffB); PG8_STAGE(PG8_SB(1, 1), b3 + hstep, voffB); PG8_STAGE(PG8_SA(1, 0), a3, voffA);
;             PG8_WAIT_V(8); PG8_WAIT_L(0); PG8_BAR; PG8_MMA(1, 0, At, B0); PG8_MMA(1, 1, At, B1); PG8_BAR; PG8_SCHED;
	s_setprio 0
	s_add_i32 s62, s62, s7
	v_lshl_add_u64 v[146:147], v[146:147], 0, s[26:27]
	s_mov_b32 m0, s62
	ds_read_b128 v[198:201], v156 offset:49152
	ds_read_b128 v[202:205], v156 offset:50176
	ds_read_b128 v[206:209], v156 offset:51200
	ds_read_b128 v[210:213], v156 offset:52224
	ds_read_b128 v[214:217], v156 offset:53248
	ds_read_b128 v[218:221], v156 offset:54272
	ds_read_b128 v[222:225], v156 offset:55296
	ds_read_b128 v[226:229], v156 offset:56320
	global_load_lds_dwordx4 v[146:147], off
	s_add_i32 m0, s62, 0x2000
	s_add_u32 s68, s84, 0x80080
	v_lshl_add_u64 v[146:147], v[148:149], 0, s[26:27]
	s_addc_u32 s69, s85, 0
	s_add_i32 s62, s66, s7
	global_load_lds_dwordx4 v[146:147], off
	v_lshl_add_u64 v[146:147], s[68:69], 0, v[134:135]
	s_mov_b32 m0, s62
	s_nop 0
	global_load_lds_dwordx4 v[146:147], off
	v_lshl_add_u64 v[146:147], s[68:69], 0, v[130:131]
	s_add_i32 m0, s62, 0x2000
	s_nop 0
	global_load_lds_dwordx4 v[146:147], off
	v_lshl_add_u64 v[146:147], v[152:153], 0, s[26:27]
	s_mov_b32 m0, s16
	s_nop 0
	global_load_lds_dwordx4 v[146:147], off
	v_lshl_add_u64 v[146:147], v[178:179], 0, s[26:27]
	s_mov_b32 m0, s17
	s_nop 0
	global_load_lds_dwordx4 v[146:147], off
	s_waitcnt vmcnt(8)
	s_waitcnt lgkmcnt(0)
	s_setprio 1
	s_barrier
	v_mfma_f32_16x16x32_bf16 v[62:65], v[142:145], v[198:201], v[62:65]
	v_mfma_f32_16x16x32_bf16 v[58:61], v[162:165], v[198:201], v[58:61]
	v_mfma_f32_16x16x32_bf16 v[46:49], v[142:145], v[206:209], v[46:49]
	v_mfma_f32_16x16x32_bf16 v[42:45], v[162:165], v[206:209], v[42:45]
	v_mfma_f32_16x16x32_bf16 v[30:33], v[142:145], v[214:217], v[30:33]
	v_mfma_f32_16x16x32_bf16 v[26:29], v[162:165], v[214:217], v[26:29]
	v_mfma_f32_16x16x32_bf16 v[14:17], v[142:145], v[222:225], v[14:17]
	v_mfma_f32_16x16x32_bf16 v[10:13], v[162:165], v[222:225], v[10:13]
	v_mfma_f32_16x16x32_bf16 v[62:65], v[158:161], v[202:205], v[62:65]
	v_mfma_f32_16x16x32_bf16 v[58:61], v[166:169], v[202:205], v[58:61]
	v_mfma_f32_16x16x32_bf16 v[46:49], v[158:161], v[210:213], v[46:49]
	v_mfma_f32_16x16x32_bf16 v[42:45], v[166:169], v[210:213], v[42:45]
	v_mfma_f32_16x16x32_bf16 v[30:33], v[158:161], v[218:221], v[30:33]
	v_mfma_f32_16x16x32_bf16 v[26:29], v[166:169], v[218:221], v[26:29]
	v_mfma_f32_16x16x32_bf16 v[14:17], v[158:161], v[226:229], v[14:17]
	v_mfma_f32_16x16x32_bf16 v[10:13], v[166:169], v[226:229], v[10:13]
	v_mfma_f32_16x16x32_bf16 v[54:57], v[170:173], v[198:201], v[54:57]
	v_mfma_f32_16x16x32_bf16 v[50:53], v[190:193], v[198:201], v[50:53]
	v_mfma_f32_16x16x32_bf16 v[38:41], v[170:173], v[206:209], v[38:41]
	v_mfma_f32_16x16x32_bf16 v[34:37], v[190:193], v[206:209], v[34:37]
	v_mfma_f32_16x16x32_bf16 v[22:25], v[170:173], v[214:217], v[22:25]
	v_mfma_f32_16x16x32_bf16 v[18:21], v[190:193], v[214:217], v[18:21]
	v_mfma_f32_16x16x32_bf16 v[6:9], v[170:173], v[222:225], v[6:9]
	v_mfma_f32_16x16x32_bf16 v[2:5], v[190:193], v[222:225], v[2:5]
	v_mfma_f32_16x16x32_bf16 v[54:57], v[174:177], v[202:205], v[54:57]
	v_mfma_f32_16x16x32_bf16 v[50:53], v[194:197], v[202:205], v[50:53]
	v_mfma_f32_16x16x32_bf16 v[38:41], v[174:177], v[210:213], v[38:41]
	v_mfma_f32_16x16x32_bf16 v[34:37], v[194:197], v[210:213], v[34:37]
	v_mfma_f32_16x16x32_bf16 v[22:25], v[174:177], v[218:221], v[22:25]
	v_mfma_f32_16x16x32_bf16 v[18:21], v[194:197], v[218:221], v[18:21]
	v_mfma_f32_16x16x32_bf16 v[6:9], v[174:177], v[226:229], v[6:9]
	v_mfma_f32_16x16x32_bf16 v[2:5], v[194:197], v[226:229], v[2:5]
	s_barrier
	s_setprio 0
	s_add_i32 s61, s61, 2
	s_add_u32 s57, s57, 0x100
	s_addc_u32 s58, s58, 0
	s_add_u32 s82, s82, 0x100
	s_addc_u32 s83, s83, 0
	s_cmp_gt_u32 s61, 29
	s_cbranch_scc0 .LBB0_151
	s_and_b64 vcc, exec, s[44:45]
	s_movk_i32 s57, 0x3df
	s_cbranch_vccz .LBB0_154
	s_barrier

; #define PG8_STAGE(bufoff, gbase, voff) do { _Pragma("unroll") for (int _i = 0; _i < 2; ++_i) \
;         __builtin_amdgcn_global_load_lds((const unsigned*)((const char*)(gbase) + (voff)[_i]), (PG8_LAS unsigned*)(lds + (bufoff) + ldsw + _i * 8192), 16, 0, 0); } while (0)
; #define PG8_LDA(dst, b, h) do { _Pragma("unroll") for (int m = 0; m < 4; ++m) _Pragma("unroll") for (int k = 0; k < 2; ++k) dst[m][k] = *(const PG8_LAS bf16x8*)(lds + PG8_SA(b, h) + aoff + m * 2048 + k * 1024); } while (0)
; #define PG8_LDB(dst, b, h) do { _Pragma("unroll") for (int n = 0; n < 2; ++n) _Pragma("unroll") for (int k = 0; k < 2; ++k) dst[n][k] = *(const PG8_LAS bf16x8*)(lds + PG8_SB(b, h) + boff + n * 2048 + k * 1024); } while (0)
; #define PG8_MMA(ai, bj, At, Bt) do { __builtin_amdgcn_s_setprio(1); _Pragma("unroll") for (int m = 0; m < 4; ++m) _Pragma("unroll") for (int n = 0; n < 2; ++n) _Pragma("unroll") for (int k = 0; k < 2; ++k) \
;         acc[ai][bj][m][n] = __builtin_amdgcn_mfma_f32_16x16x32_bf16(Bt[n][k], At[m][k], acc[ai][bj][m][n], 0, 0, 0); __builtin_amdgcn_s_setprio(0); } while (0)
; #define PG8_BAR __builtin_amdgcn_s_barrier()
; template <class Epi, class Sched, bool ALIGN_EPI = false, bool SP2 = false>
; __device__ __forceinline__ void gemm_phase(PG8_LAS unsigned char* lds, const Gemm g, const Sched& S, const Epi& E, const int wv) {
;     ...
;             PG8_LDB(B0, 0, 0); PG8_LDB(B1, 0, 1); PG8_SCHED; PG8_LDA(At, 0, 0); PG8_STAGE(PG8_SA(1, 1), a1 + hstep, voffA);
;             PG8_WAIT_V(8); PG8_WAIT_L(0); PG8_BAR; PG8_MMA(0, 0, At, B0); PG8_MMA(0, 1, At, B1); PG8_BAR; PG8_SCHED;
;             PG8_LDA(At, 0, 1); PG8_STAGE(PG8_SB(0, 0), b2, voffB); PG8_STAGE(PG8_SB(0, 1), b2 + hstep, voffB); PG8_STAGE(PG8_SA(0, 0), a2, voffA);
;             PG8_WAIT_V(8); PG8_WAIT_L(0); PG8_BAR; PG8_MMA(1, 0, At, B0); PG8_MMA(1, 1, At, B1); PG8_BAR; PG8_SCHED;
;             PG8_LDB(B0, 1, 0); PG8_LDB(B1, 1, 1); PG8_SCHED; PG8_LDA(At, 1, 0); PG8_STAGE(PG8_SA(0, 1), a2 + hstep, voffA);
;             PG8_WAIT_V(8); PG8_WAIT_L(0); PG8_BAR; PG8_MMA(0, 0, At, B0); PG8_MMA(0, 1, At, B1); PG8_BAR; PG8_SCHED;
;             PG8_LDA(At, 1, 1); PG8_STAGE(PG8_SB(1, 0), b3, voffB); PG8_STAGE(PG8_SB(1, 1), b3 + hstep, voffB); PG8_STAGE(PG8_SA(1, 0), a3, voffA);
;             PG8_WAIT_V(8); PG8_WAIT_L(0); PG8_BAR; PG8_MMA(1, 0, At, B0); PG8_MMA(1, 1, At, B1); PG8_BAR; PG8_SCHED;
.LBB0_169:
	s_add_u32 s35, s9, s74
	s_addc_u32 s41, s14, s75
	s_and_b64 s[0:1], s[0:1], exec
	s_cselect_b32 s1, s41, s85
	s_cselect_b32 s0, s35, s84
	s_add_i32 s35, 0, 0x10000
	s_add_i32 s41, 0, 0x14000
	v_add_u32_e32 v14, s35, v0
	v_add_u32_e32 v30, s41, v0
	ds_read_b128 v[2:5], v14
	ds_read_b128 v[6:9], v14 offset:1024
	ds_read_b128 v[10:13], v14 offset:2048
	ds_read_b128 v[14:17], v14 offset:3072
	ds_read_b128 v[18:21], v30
	ds_read_b128 v[22:25], v30 offset:1024
	ds_read_b128 v[26:29], v30 offset:2048
	ds_read_b128 v[30:33], v30 offset:3072
	s_add_u32 s68, s84, 0x80080
	s_addc_u32 s69, s85, 0
	v_lshl_add_u64 v[78:79], s[68:69], 0, v[72:73]
	s_add_i32 m0, s8, 0xc000
	ds_read_b128 v[34:37], v77
	ds_read_b128 v[38:41], v77 offset:1024
	ds_read_b128 v[42:45], v77 offset:2048
	ds_read_b128 v[46:49], v77 offset:3072
	ds_read_b128 v[50:53], v77 offset:4096
	ds_read_b128 v[54:57], v77 offset:5120
	ds_read_b128 v[58:61], v77 offset:6144
	ds_read_b128 v[62:65], v77 offset:7168
	global_load_lds_dwordx4 v[78:79], off
	v_lshl_add_u64 v[78:79], s[68:69], 0, v[68:69]
	s_add_i32 m0, s8, 0xe000
	s_nop 0
	global_load_lds_dwordx4 v[78:79], off
	s_waitcnt vmcnt(8)
	s_waitcnt lgkmcnt(0)
	s_setprio 1
	s_barrier
	v_mfma_f32_16x16x32_bf16 v[78:81], v[2:5], v[34:37], 0
	v_mfma_f32_16x16x32_bf16 v[86:89], v[2:5], v[42:45], 0
	v_mfma_f32_16x16x32_bf16 v[94:97], v[2:5], v[50:53], 0
	v_mfma_f32_16x16x32_bf16 v[2:5], v[2:5], v[58:61], 0
	v_mfma_f32_16x16x32_bf16 v[78:81], v[6:9], v[38:41], v[78:81]
	v_mfma_f32_16x16x32_bf16 v[86:89], v[6:9], v[46:49], v[86:89]
	v_mfma_f32_16x16x32_bf16 v[94:97], v[6:9], v[54:57], v[94:97]
	v_mfma_f32_16x16x32_bf16 v[2:5], v[6:9], v[62:65], v[2:5]
	v_mfma_f32_16x16x32_bf16 v[6:9], v[10:13], v[58:61], 0
	v_mfma_f32_16x16x32_bf16 v[82:85], v[10:13], v[34:37], 0
	v_mfma_f32_16x16x32_bf16 v[90:93], v[10:13], v[42:45], 0
	v_mfma_f32_16x16x32_bf16 v[98:101], v[10:13], v[50:53], 0
	v_mfma_f32_16x16x32_bf16 v[6:9], v[14:17], v[62:65], v[6:9]
	v_mfma_f32_16x16x32_bf16 v[82:85], v[14:17], v[38:41], v[82:85]
	v_mfma_f32_16x16x32_bf16 v[90:93], v[14:17], v[46:49], v[90:93]
	v_mfma_f32_16x16x32_bf16 v[98:101], v[14:17], v[54:57], v[98:101]
	v_mfma_f32_16x16x32_bf16 v[10:13], v[18:21], v[34:37], 0
	v_mfma_f32_16x16x32_bf16 v[102:105], v[22:25], v[38:41], v[10:13]
	v_mfma_f32_16x16x32_bf16 v[10:13], v[26:29], v[34:37], 0
	v_mfma_f32_16x16x32_bf16 v[106:109], v[30:33], v[38:41], v[10:13]
	v_mfma_f32_16x16x32_bf16 v[10:13], v[18:21], v[42:45], 0
	v_mfma_f32_16x16x32_bf16 v[110:113], v[22:25], v[46:49], v[10:13]
	v_mfma_f32_16x16x32_bf16 v[10:13], v[26:29], v[42:45], 0
	v_mfma_f32_16x16x32_bf16 v[42:45], v[30:33], v[46:49], v[10:13]
	v_mfma_f32_16x16x32_bf16 v[10:13], v[18:21], v[50:53], 0
	v_mfma_f32_16x16x32_bf16 v[46:49], v[22:25], v[54:57], v[10:13]
	v_mfma_f32_16x16x32_bf16 v[10:13], v[26:29], v[50:53], 0
	v_mfma_f32_16x16x32_bf16 v[114:117], v[30:33], v[54:57], v[10:13]
	v_mfma_f32_16x16x32_bf16 v[10:13], v[18:21], v[58:61], 0
	v_mfma_f32_16x16x32_bf16 v[118:121], v[22:25], v[62:65], v[10:13]
	v_mfma_f32_16x16x32_bf16 v[10:13], v[26:29], v[58:61], 0
	v_mfma_f32_16x16x32_bf16 v[30:33], v[30:33], v[62:65], v[10:13]
	s_barrier
	s_setprio 0
	s_add_i32 s35, s35, s7
	v_lshl_add_u64 v[146:147], s[44:45], 0, v[70:71]
	s_mov_b32 m0, s35
	v_lshl_add_u64 v[148:149], s[44:45], 0, v[66:67]
	global_load_lds_dwordx4 v[146:147], off
	s_add_i32 m0, s35, 0x2000
	s_add_u32 s68, s44, 0x80000
	s_addc_u32 s69, s45, 0
	s_add_i32 s35, s41, s7
	global_load_lds_dwordx4 v[148:149], off
	v_lshl_add_u64 v[10:11], s[68:69], 0, v[70:71]
	s_mov_b32 m0, s35
	v_lshl_add_u64 v[172:173], s[0:1], 0, v[72:73]
	global_load_lds_dwordx4 v[10:11], off
	v_lshl_add_u64 v[10:11], s[68:69], 0, v[66:67]
	s_add_i32 m0, s35, 0x2000
	v_lshl_add_u64 v[174:175], s[0:1], 0, v[68:69]
	global_load_lds_dwordx4 v[10:11], off
	s_mov_b32 m0, s8
	s_nop 0
	global_load_lds_dwordx4 v[172:173], off
	s_mov_b32 m0, s15
	s_nop 0
	global_load_lds_dwordx4 v[174:175], off
	s_waitcnt vmcnt(8)
	s_waitcnt lgkmcnt(0)
	s_barrier
	s_setprio 1
	s_setprio 0
	s_setprio 1
	s_setprio 0
	s_barrier
; #define PG8_STAGE(bufoff, gbase, voff) do { _Pragma("unroll") for (int _i = 0; _i < 2; ++_i) \
;         __builtin_amdgcn_global_load_lds((const unsigned*)((const char*)(gbase) + (voff)[_i]), (PG8_LAS unsigned*)(lds + (bufoff) + ldsw + _i * 8192), 16, 0, 0); } while (0)
; #define PG8_LDA(dst, b, h) do { _Pragma("unroll") for (int m = 0; m < 4; ++m) _Pragma("unroll") for (int k = 0; k < 2; ++k) dst[m][k] = *(const PG8_LAS bf16x8*)(lds + PG8_SA(b, h) + aoff + m * 2048 + k * 1024); } while (0)
; #define PG8_LDB(dst, b, h) do { _Pragma("unroll") for (int n = 0; n < 2; ++n) _Pragma("unroll") for (int k = 0; k < 2; ++k) dst[n][k] = *(const PG8_LAS bf16x8*)(lds + PG8_SB(b, h) + boff + n * 2048 + k * 1024); } while (0)
; #define PG8_MMA(ai, bj, At, Bt) do { __builtin_amdgcn_s_setprio(1); _Pragma("unroll") for (int m = 0; m < 4; ++m) _Pragma("unroll") for (int n = 0; n < 2; ++n) _Pragma("unroll") for (int k = 0; k < 2; ++k) \
;         acc[ai][bj][m][n] = __builtin_amdgcn_mfma_f32_16x16x32_bf16(Bt[n][k], At[m][k], acc[ai][bj][m][n], 0, 0, 0); __builtin_amdgcn_s_setprio(0); } while (0)
; #define PG8_WAIT_V(n) asm volatile("s_waitcnt vmcnt(" #n ")" ::: "memory")
; #define PG8_WAIT_L(n) asm volatile("s_waitcnt lgkmcnt(" #n ")" ::: "memory")
; #define PG8_BAR __builtin_amdgcn_s_barrier()
; #define PG8_SCHED __builtin_amdgcn_sched_barrier(0)
; template <class Epi, class Sched, bool ALIGN_EPI = false, bool SP2 = false>
; __device__ __forceinline__ void gemm_phase(PG8_LAS unsigned char* lds, const Gemm g, const Sched& S, const Epi& E, const int wv) {
;     ...
;             PG8_WAIT_V(8); PG8_WAIT_L(0); PG8_BAR; PG8_MMA(1, 0, At, B0); PG8_MMA(1, 1, At, B1); PG8_BAR; PG8_SCHED;
;             PG8_LDB(B0, 1, 0); PG8_LDB(B1, 1, 1); PG8_SCHED; PG8_LDA(At, 1, 0); PG8_STAGE(PG8_SA(0, 1), a2 + hstep, voffA);
;             PG8_WAIT_V(8); PG8_WAIT_L(0); PG8_BAR; PG8_MMA(0, 0, At, B0); PG8_MMA(0, 1, At, B1); PG8_BAR; PG8_SCHED;
;             PG8_LDA(At, 1, 1); PG8_STAGE(PG8_SB(1, 0), b3, voffB); PG8_STAGE(PG8_SB(1, 1), b3 + hstep, voffB); PG8_STAGE(PG8_SA(1, 0), a3, voffA);
;             PG8_WAIT_V(8); PG8_WAIT_L(0); PG8_BAR; PG8_MMA(1, 0, At, B0); PG8_MMA(1, 1, At, B1); PG8_BAR; PG8_SCHED;
	s_add_i32 s35, 0, 0x18000
	v_add_u32_e32 v10, s35, v0
	s_add_i32 s41, 0, 0x1c000
	ds_read_b128 v[26:29], v10
	ds_read_b128 v[50:53], v10 offset:1024
	ds_read_b128 v[54:57], v10 offset:2048
	ds_read_b128 v[58:61], v10 offset:3072
	v_add_u32_e32 v10, s41, v0
	ds_read_b128 v[122:125], v10
	ds_read_b128 v[126:129], v10 offset:1024
	ds_read_b128 v[130:133], v10 offset:2048
	ds_read_b128 v[134:137], v10 offset:3072
	s_add_u32 s68, s0, 0x80000
	s_addc_u32 s69, s1, 0
	s_mov_b32 m0, s16
	v_lshl_add_u64 v[10:11], s[68:69], 0, v[72:73]
	ds_read_b128 v[62:65], v77 offset:32768
	ds_read_b128 v[138:141], v77 offset:33792
	ds_read_b128 v[142:145], v77 offset:34816
	ds_read_b128 v[152:155], v77 offset:35840
	ds_read_b128 v[156:159], v77 offset:36864
	ds_read_b128 v[160:163], v77 offset:37888
	ds_read_b128 v[164:167], v77 offset:38912
	ds_read_b128 v[168:171], v77 offset:39936
	global_load_lds_dwordx4 v[10:11], off
	v_lshl_add_u64 v[10:11], s[68:69], 0, v[68:69]
	s_mov_b32 m0, s17
	s_nop 0
	global_load_lds_dwordx4 v[10:11], off
	s_waitcnt vmcnt(8)
	s_waitcnt lgkmcnt(0)
	s_setprio 1
	s_barrier
	v_mfma_f32_16x16x32_bf16 v[10:13], v[26:29], v[62:65], v[78:81]
	v_mfma_f32_16x16x32_bf16 v[34:37], v[50:53], v[138:141], v[10:13]
	v_mfma_f32_16x16x32_bf16 v[10:13], v[54:57], v[62:65], v[82:85]
	v_mfma_f32_16x16x32_bf16 v[38:41], v[58:61], v[138:141], v[10:13]
	v_mfma_f32_16x16x32_bf16 v[10:13], v[26:29], v[142:145], v[86:89]
	v_mfma_f32_16x16x32_bf16 v[18:21], v[50:53], v[152:155], v[10:13]
	v_mfma_f32_16x16x32_bf16 v[10:13], v[54:57], v[142:145], v[90:93]
	v_mfma_f32_16x16x32_bf16 v[22:25], v[58:61], v[152:155], v[10:13]
	v_mfma_f32_16x16x32_bf16 v[10:13], v[26:29], v[156:159], v[94:97]
	v_mfma_f32_16x16x32_bf16 v[14:17], v[54:57], v[156:159], v[98:101]
	v_mfma_f32_16x16x32_bf16 v[2:5], v[26:29], v[164:167], v[2:5]
	v_mfma_f32_16x16x32_bf16 v[6:9], v[54:57], v[164:167], v[6:9]
	v_mfma_f32_16x16x32_bf16 v[10:13], v[50:53], v[160:163], v[10:13]
	v_mfma_f32_16x16x32_bf16 v[14:17], v[58:61], v[160:163], v[14:17]
	v_mfma_f32_16x16x32_bf16 v[2:5], v[50:53], v[168:171], v[2:5]
	v_mfma_f32_16x16x32_bf16 v[6:9], v[58:61], v[168:171], v[6:9]
	v_mfma_f32_16x16x32_bf16 v[26:29], v[122:125], v[62:65], v[102:105]
	v_mfma_f32_16x16x32_bf16 v[58:61], v[126:129], v[138:141], v[26:29]
	v_mfma_f32_16x16x32_bf16 v[26:29], v[130:133], v[62:65], v[106:109]
	v_mfma_f32_16x16x32_bf16 v[62:65], v[134:137], v[138:141], v[26:29]
	v_mfma_f32_16x16x32_bf16 v[26:29], v[122:125], v[142:145], v[110:113]
	v_mfma_f32_16x16x32_bf16 v[50:53], v[126:129], v[152:155], v[26:29]
	v_mfma_f32_16x16x32_bf16 v[26:29], v[130:133], v[142:145], v[42:45]
	v_mfma_f32_16x16x32_bf16 v[54:57], v[134:137], v[152:155], v[26:29]
	v_mfma_f32_16x16x32_bf16 v[26:29], v[122:125], v[156:159], v[46:49]
	v_mfma_f32_16x16x32_bf16 v[42:45], v[126:129], v[160:163], v[26:29]
	v_mfma_f32_16x16x32_bf16 v[26:29], v[130:133], v[156:159], v[114:117]
	v_mfma_f32_16x16x32_bf16 v[46:49], v[134:137], v[160:163], v[26:29]
	v_mfma_f32_16x16x32_bf16 v[26:29], v[122:125], v[164:167], v[118:121]
	v_mfma_f32_16x16x32_bf16 v[30:33], v[130:133], v[164:167], v[30:33]
	v_mfma_f32_16x16x32_bf16 v[26:29], v[126:129], v[168:171], v[26:29]
	v_mfma_f32_16x16x32_bf16 v[30:33], v[134:137], v[168:171], v[30:33]
	s_barrier
	s_setprio 0
	s_add_i32 s35, s35, s7
	v_lshl_add_u64 v[78:79], v[146:147], 0, s[26:27]
	s_mov_b32 m0, s35
	s_nop 0
	global_load_lds_dwordx4 v[78:79], off
	s_add_i32 m0, s35, 0x2000
	s_add_u32 s68, s44, 0x80080
	v_lshl_add_u64 v[78:79], v[148:149], 0, s[26:27]
	s_addc_u32 s69, s45, 0
	s_add_i32 s35, s41, s7
	global_load_lds_dwordx4 v[78:79], off
	v_lshl_add_u64 v[78:79], s[68:69], 0, v[70:71]
	s_mov_b32 m0, s35
	s_nop 0
	global_load_lds_dwordx4 v[78:79], off
	v_lshl_add_u64 v[78:79], s[68:69], 0, v[66:67]
	s_add_i32 m0, s35, 0x2000
	s_nop 0
	global_load_lds_dwordx4 v[78:79], off
	v_lshl_add_u64 v[78:79], v[172:173], 0, s[26:27]
	s_mov_b32 m0, s22
	s_nop 0
	global_load_lds_dwordx4 v[78:79], off
	v_lshl_add_u64 v[78:79], v[174:175], 0, s[26:27]
	s_mov_b32 m0, s23
	s_nop 0
	global_load_lds_dwordx4 v[78:79], off
	s_waitcnt vmcnt(8)
	s_waitcnt lgkmcnt(0)
	s_barrier
	s_setprio 1
	s_setprio 0
	s_setprio 1
	s_setprio 0
	s_barrier
	s_andn2_b64 vcc, exec, s[48:49]
	s_cbranch_vccnz .LBB0_171
	s_barrier

; #define PG8_STAGE(bufoff, gbase, voff) do { _Pragma("unroll") for (int _i = 0; _i < 2; ++_i) \
;         __builtin_amdgcn_global_load_lds((const unsigned*)((const char*)(gbase) + (voff)[_i]), (PG8_LAS unsigned*)(lds + (bufoff) + ldsw + _i * 8192), 16, 0, 0); } while (0)
; #define PG8_LDA(dst, b, h) do { _Pragma("unroll") for (int m = 0; m < 4; ++m) _Pragma("unroll") for (int k = 0; k < 2; ++k) dst[m][k] = *(const PG8_LAS bf16x8*)(lds + PG8_SA(b, h) + aoff + m * 2048 + k * 1024); } while (0)
; #define PG8_LDB(dst, b, h) do { _Pragma("unroll") for (int n = 0; n < 2; ++n) _Pragma("unroll") for (int k = 0; k < 2; ++k) dst[n][k] = *(const PG8_LAS bf16x8*)(lds + PG8_SB(b, h) + boff + n * 2048 + k * 1024); } while (0)
; #define PG8_MMA(ai, bj, At, Bt) do { __builtin_amdgcn_s_setprio(1); _Pragma("unroll") for (int m = 0; m < 4; ++m) _Pragma("unroll") for (int n = 0; n < 2; ++n) _Pragma("unroll") for (int k = 0; k < 2; ++k) \
;         acc[ai][bj][m][n] = __builtin_amdgcn_mfma_f32_16x16x32_bf16(Bt[n][k], At[m][k], acc[ai][bj][m][n], 0, 0, 0); __builtin_amdgcn_s_setprio(0); } while (0)
; #define PG8_WAIT_V(n) asm volatile("s_waitcnt vmcnt(" #n ")" ::: "memory")
; #define PG8_WAIT_L(n) asm volatile("s_waitcnt lgkmcnt(" #n ")" ::: "memory")
; #define PG8_BAR __builtin_amdgcn_s_barrier()
; #define PG8_SCHED __builtin_amdgcn_sched_barrier(0)
; template <class Epi, class Sched, bool ALIGN_EPI = false, bool SP2 = false>
; __device__ __forceinline__ void gemm_phase(PG8_LAS unsigned char* lds, const Gemm g, const Sched& S, const Epi& E, const int wv) {
;     ...
;             PG8_LDB(B0, 0, 0); PG8_LDB(B1, 0, 1); PG8_SCHED; PG8_LDA(At, 0, 0); PG8_STAGE(PG8_SA(1, 1), a1 + hstep, voffA);
;             PG8_WAIT_V(8); PG8_WAIT_L(0); PG8_BAR; PG8_MMA(0, 0, At, B0); PG8_MMA(0, 1, At, B1); PG8_BAR; PG8_SCHED;
;             PG8_LDA(At, 0, 1); PG8_STAGE(PG8_SB(0, 0), b2, voffB); PG8_STAGE(PG8_SB(0, 1), b2 + hstep, voffB); PG8_STAGE(PG8_SA(0, 0), a2, voffA);
;             PG8_WAIT_V(8); PG8_WAIT_L(0); PG8_BAR; PG8_MMA(1, 0, At, B0); PG8_MMA(1, 1, At, B1); PG8_BAR; PG8_SCHED;
.LBB0_957:
	s_add_u32 s84, s0, 0xfff80080
	s_addc_u32 s85, s1, -1
	s_add_i32 s89, 0, 0x10000
	s_cmp_eq_u32 s88, 28
	s_cselect_b32 s87, s34, s85
	s_cselect_b32 s86, s35, s84
	v_add_u32_e32 v0, s89, v190
	s_cselect_b32 s85, s43, s83
	s_cselect_b32 s84, s75, s77
	s_add_i32 vcc_lo, 0, 0x14000
	ds_read_b128 v[166:169], v0
	ds_read_b128 v[170:173], v0 offset:1024
	ds_read_b128 v[174:177], v0 offset:2048
	ds_read_b128 v[194:197], v0 offset:3072
	v_add_u32_e32 v0, vcc_lo, v190
	ds_read_b128 v[198:201], v0
	ds_read_b128 v[202:205], v0 offset:1024
	ds_read_b128 v[206:209], v0 offset:2048
	ds_read_b128 v[210:213], v0 offset:3072
	v_lshl_add_u64 v[178:179], s[0:1], 0, v[164:165]
	s_add_i32 m0, s66, 0xc000
	ds_read_b128 v[214:217], v192
	ds_read_b128 v[218:221], v192 offset:1024
	ds_read_b128 v[222:225], v192 offset:2048
	ds_read_b128 v[226:229], v192 offset:3072
	ds_read_b128 v[230:233], v192 offset:4096
	ds_read_b128 v[234:237], v192 offset:5120
	ds_read_b128 v[238:241], v192 offset:6144
	ds_read_b128 v[242:245], v192 offset:7168
	global_load_lds_dwordx4 v[178:179], off
	v_lshl_add_u64 v[178:179], s[0:1], 0, v[162:163]
	s_add_i32 m0, s66, 0xe000
	s_nop 0
	global_load_lds_dwordx4 v[178:179], off
	s_waitcnt vmcnt(8)
	s_waitcnt lgkmcnt(0)
	s_setprio 1
	s_barrier
	v_mfma_f32_16x16x32_bf16 v[126:129], v[166:169], v[214:217], v[126:129]
	v_mfma_f32_16x16x32_bf16 v[122:125], v[174:177], v[214:217], v[122:125]
	v_mfma_f32_16x16x32_bf16 v[110:113], v[166:169], v[222:225], v[110:113]
	v_mfma_f32_16x16x32_bf16 v[106:109], v[174:177], v[222:225], v[106:109]
	v_mfma_f32_16x16x32_bf16 v[94:97], v[166:169], v[230:233], v[94:97]
	v_mfma_f32_16x16x32_bf16 v[90:93], v[174:177], v[230:233], v[90:93]
	v_mfma_f32_16x16x32_bf16 v[78:81], v[166:169], v[238:241], v[78:81]
	v_mfma_f32_16x16x32_bf16 v[74:77], v[174:177], v[238:241], v[74:77]
	v_mfma_f32_16x16x32_bf16 v[126:129], v[170:173], v[218:221], v[126:129]
	v_mfma_f32_16x16x32_bf16 v[122:125], v[194:197], v[218:221], v[122:125]
	v_mfma_f32_16x16x32_bf16 v[110:113], v[170:173], v[226:229], v[110:113]
	v_mfma_f32_16x16x32_bf16 v[106:109], v[194:197], v[226:229], v[106:109]
	v_mfma_f32_16x16x32_bf16 v[94:97], v[170:173], v[234:237], v[94:97]
	v_mfma_f32_16x16x32_bf16 v[90:93], v[194:197], v[234:237], v[90:93]
	v_mfma_f32_16x16x32_bf16 v[78:81], v[170:173], v[242:245], v[78:81]
	v_mfma_f32_16x16x32_bf16 v[74:77], v[194:197], v[242:245], v[74:77]
	v_mfma_f32_16x16x32_bf16 v[118:121], v[198:201], v[214:217], v[118:121]
	v_mfma_f32_16x16x32_bf16 v[114:117], v[206:209], v[214:217], v[114:117]
	v_mfma_f32_16x16x32_bf16 v[102:105], v[198:201], v[222:225], v[102:105]
	v_mfma_f32_16x16x32_bf16 v[98:101], v[206:209], v[222:225], v[98:101]
	v_mfma_f32_16x16x32_bf16 v[86:89], v[198:201], v[230:233], v[86:89]
	v_mfma_f32_16x16x32_bf16 v[82:85], v[206:209], v[230:233], v[82:85]
	v_mfma_f32_16x16x32_bf16 v[70:73], v[198:201], v[238:241], v[70:73]
	v_mfma_f32_16x16x32_bf16 v[66:69], v[206:209], v[238:241], v[66:69]
	v_mfma_f32_16x16x32_bf16 v[118:121], v[202:205], v[218:221], v[118:121]
	v_mfma_f32_16x16x32_bf16 v[114:117], v[210:213], v[218:221], v[114:117]
	v_mfma_f32_16x16x32_bf16 v[102:105], v[202:205], v[226:229], v[102:105]
	v_mfma_f32_16x16x32_bf16 v[98:101], v[210:213], v[226:229], v[98:101]
	v_mfma_f32_16x16x32_bf16 v[86:89], v[202:205], v[234:237], v[86:89]
	v_mfma_f32_16x16x32_bf16 v[82:85], v[210:213], v[234:237], v[82:85]
	v_mfma_f32_16x16x32_bf16 v[70:73], v[202:205], v[242:245], v[70:73]
	v_mfma_f32_16x16x32_bf16 v[66:69], v[210:213], v[242:245], v[66:69]
	s_barrier
	s_setprio 0
	s_add_i32 s89, s89, s57
	v_lshl_add_u64 v[178:179], s[84:85], 0, v[132:133]
	s_mov_b32 m0, s89
	ds_read_b128 v[214:217], v192 offset:16384
	ds_read_b128 v[218:221], v192 offset:17408
	ds_read_b128 v[222:225], v192 offset:18432
	ds_read_b128 v[226:229], v192 offset:19456
	ds_read_b128 v[230:233], v192 offset:20480
	ds_read_b128 v[234:237], v192 offset:21504
	ds_read_b128 v[238:241], v192 offset:22528
	ds_read_b128 v[242:245], v192 offset:23552
	global_load_lds_dwordx4 v[178:179], off
	s_add_i32 m0, s89, 0x2000
	s_add_u32 s90, s84, 0x80000
	v_lshl_add_u64 v[246:247], s[84:85], 0, v[136:137]
	s_addc_u32 s91, s85, 0
	s_add_i32 s89, vcc_lo, s57
	global_load_lds_dwordx4 v[246:247], off
	v_lshl_add_u64 v[248:249], s[90:91], 0, v[132:133]
	s_mov_b32 m0, s89
	v_lshl_add_u64 v[146:147], s[86:87], 0, v[134:135]
	global_load_lds_dwordx4 v[248:249], off
	v_lshl_add_u64 v[248:249], s[90:91], 0, v[136:137]
	s_add_i32 m0, s89, 0x2000
	s_nop 0
	global_load_lds_dwordx4 v[248:249], off
	v_lshl_add_u64 v[248:249], s[86:87], 0, v[130:131]
	s_mov_b32 m0, s66
	s_nop 0
	global_load_lds_dwordx4 v[248:249], off
	s_mov_b32 m0, s61
	s_nop 0
	global_load_lds_dwordx4 v[146:147], off
	s_waitcnt vmcnt(8)
	s_waitcnt lgkmcnt(0)
	s_setprio 1
	s_barrier
; #define PG8_STAGE(bufoff, gbase, voff) do { _Pragma("unroll") for (int _i = 0; _i < 2; ++_i) \
;         __builtin_amdgcn_global_load_lds((const unsigned*)((const char*)(gbase) + (voff)[_i]), (PG8_LAS unsigned*)(lds + (bufoff) + ldsw + _i * 8192), 16, 0, 0); } while (0)
; #define PG8_LDA(dst, b, h) do { _Pragma("unroll") for (int m = 0; m < 4; ++m) _Pragma("unroll") for (int k = 0; k < 2; ++k) dst[m][k] = *(const PG8_LAS bf16x8*)(lds + PG8_SA(b, h) + aoff + m * 2048 + k * 1024); } while (0)
; #define PG8_LDB(dst, b, h) do { _Pragma("unroll") for (int n = 0; n < 2; ++n) _Pragma("unroll") for (int k = 0; k < 2; ++k) dst[n][k] = *(const PG8_LAS bf16x8*)(lds + PG8_SB(b, h) + boff + n * 2048 + k * 1024); } while (0)
; #define PG8_MMA(ai, bj, At, Bt) do { __builtin_amdgcn_s_setprio(1); _Pragma("unroll") for (int m = 0; m < 4; ++m) _Pragma("unroll") for (int n = 0; n < 2; ++n) _Pragma("unroll") for (int k = 0; k < 2; ++k) \
;         acc[ai][bj][m][n] = __builtin_amdgcn_mfma_f32_16x16x32_bf16(Bt[n][k], At[m][k], acc[ai][bj][m][n], 0, 0, 0); __builtin_amdgcn_s_setprio(0); } while (0)
; #define PG8_WAIT_V(n) asm volatile("s_waitcnt vmcnt(" #n ")" ::: "memory")
; #define PG8_WAIT_L(n) asm volatile("s_waitcnt lgkmcnt(" #n ")" ::: "memory")
; #define PG8_BAR __builtin_amdgcn_s_barrier()
; #define PG8_SCHED __builtin_amdgcn_sched_barrier(0)
; template <class Epi, class Sched, bool ALIGN_EPI = false, bool SP2 = false>
; __device__ __forceinline__ void gemm_phase(PG8_LAS unsigned char* lds, const Gemm g, const Sched& S, const Epi& E, const int wv) {
;     ...
;             PG8_WAIT_V(8); PG8_WAIT_L(0); PG8_BAR; PG8_MMA(1, 0, At, B0); PG8_MMA(1, 1, At, B1); PG8_BAR; PG8_SCHED;
;             PG8_LDB(B0, 1, 0); PG8_LDB(B1, 1, 1); PG8_SCHED; PG8_LDA(At, 1, 0); PG8_STAGE(PG8_SA(0, 1), a2 + hstep, voffA);
;             PG8_WAIT_V(8); PG8_WAIT_L(0); PG8_BAR; PG8_MMA(0, 0, At, B0); PG8_MMA(0, 1, At, B1); PG8_BAR; PG8_SCHED;
	v_mfma_f32_16x16x32_bf16 v[62:65], v[166:169], v[214:217], v[62:65]
	v_mfma_f32_16x16x32_bf16 v[58:61], v[174:177], v[214:217], v[58:61]
	v_mfma_f32_16x16x32_bf16 v[46:49], v[166:169], v[222:225], v[46:49]
	v_mfma_f32_16x16x32_bf16 v[42:45], v[174:177], v[222:225], v[42:45]
	v_mfma_f32_16x16x32_bf16 v[30:33], v[166:169], v[230:233], v[30:33]
	v_mfma_f32_16x16x32_bf16 v[26:29], v[174:177], v[230:233], v[26:29]
	v_mfma_f32_16x16x32_bf16 v[14:17], v[166:169], v[238:241], v[14:17]
	v_mfma_f32_16x16x32_bf16 v[10:13], v[174:177], v[238:241], v[10:13]
	v_mfma_f32_16x16x32_bf16 v[62:65], v[170:173], v[218:221], v[62:65]
	v_mfma_f32_16x16x32_bf16 v[58:61], v[194:197], v[218:221], v[58:61]
	v_mfma_f32_16x16x32_bf16 v[46:49], v[170:173], v[226:229], v[46:49]
	v_mfma_f32_16x16x32_bf16 v[42:45], v[194:197], v[226:229], v[42:45]
	v_mfma_f32_16x16x32_bf16 v[30:33], v[170:173], v[234:237], v[30:33]
	v_mfma_f32_16x16x32_bf16 v[26:29], v[194:197], v[234:237], v[26:29]
	v_mfma_f32_16x16x32_bf16 v[14:17], v[170:173], v[242:245], v[14:17]
	v_mfma_f32_16x16x32_bf16 v[10:13], v[194:197], v[242:245], v[10:13]
	v_mfma_f32_16x16x32_bf16 v[54:57], v[198:201], v[214:217], v[54:57]
	v_mfma_f32_16x16x32_bf16 v[50:53], v[206:209], v[214:217], v[50:53]
	v_mfma_f32_16x16x32_bf16 v[38:41], v[198:201], v[222:225], v[38:41]
	v_mfma_f32_16x16x32_bf16 v[34:37], v[206:209], v[222:225], v[34:37]
	v_mfma_f32_16x16x32_bf16 v[22:25], v[198:201], v[230:233], v[22:25]
	v_mfma_f32_16x16x32_bf16 v[18:21], v[206:209], v[230:233], v[18:21]
	v_mfma_f32_16x16x32_bf16 v[6:9], v[198:201], v[238:241], v[6:9]
	v_mfma_f32_16x16x32_bf16 v[2:5], v[206:209], v[238:241], v[2:5]
	v_mfma_f32_16x16x32_bf16 v[54:57], v[202:205], v[218:221], v[54:57]
	v_mfma_f32_16x16x32_bf16 v[50:53], v[210:213], v[218:221], v[50:53]
	v_mfma_f32_16x16x32_bf16 v[38:41], v[202:205], v[226:229], v[38:41]
	v_mfma_f32_16x16x32_bf16 v[34:37], v[210:213], v[226:229], v[34:37]
	v_mfma_f32_16x16x32_bf16 v[22:25], v[202:205], v[234:237], v[22:25]
	v_mfma_f32_16x16x32_bf16 v[18:21], v[210:213], v[234:237], v[18:21]
	v_mfma_f32_16x16x32_bf16 v[6:9], v[202:205], v[242:245], v[6:9]
	v_mfma_f32_16x16x32_bf16 v[2:5], v[210:213], v[242:245], v[2:5]
	s_barrier
	s_setprio 0
	s_add_i32 s89, 0, 0x18000
	v_add_u32_e32 v0, s89, v190
	s_add_i32 s90, 0, 0x1c000
	ds_read_b128 v[166:169], v0
	ds_read_b128 v[170:173], v0 offset:1024
	ds_read_b128 v[174:177], v0 offset:2048
	ds_read_b128 v[194:197], v0 offset:3072
	v_add_u32_e32 v0, s90, v190
	ds_read_b128 v[198:201], v0
	ds_read_b128 v[202:205], v0 offset:1024
	ds_read_b128 v[206:209], v0 offset:2048
	ds_read_b128 v[210:213], v0 offset:3072
	s_add_u32 s86, s86, 0x80000
	s_addc_u32 s87, s87, 0
	s_mov_b32 m0, s62
	v_lshl_add_u64 v[148:149], s[86:87], 0, v[130:131]
	ds_read_b128 v[214:217], v192 offset:32768
	ds_read_b128 v[218:221], v192 offset:33792
	ds_read_b128 v[222:225], v192 offset:34816
	ds_read_b128 v[226:229], v192 offset:35840
	ds_read_b128 v[230:233], v192 offset:36864
	ds_read_b128 v[234:237], v192 offset:37888
	ds_read_b128 v[238:241], v192 offset:38912
	ds_read_b128 v[242:245], v192 offset:39936
	global_load_lds_dwordx4 v[148:149], off
	v_lshl_add_u64 v[148:149], s[86:87], 0, v[134:135]
	s_mov_b32 m0, s58
	s_nop 0
	global_load_lds_dwordx4 v[148:149], off
	s_waitcnt vmcnt(8)
	s_waitcnt lgkmcnt(0)
	s_setprio 1
	s_barrier
	v_mfma_f32_16x16x32_bf16 v[126:129], v[166:169], v[214:217], v[126:129]
	v_mfma_f32_16x16x32_bf16 v[122:125], v[174:177], v[214:217], v[122:125]
	v_mfma_f32_16x16x32_bf16 v[110:113], v[166:169], v[222:225], v[110:113]
	v_mfma_f32_16x16x32_bf16 v[106:109], v[174:177], v[222:225], v[106:109]
	v_mfma_f32_16x16x32_bf16 v[94:97], v[166:169], v[230:233], v[94:97]
	v_mfma_f32_16x16x32_bf16 v[90:93], v[174:177], v[230:233], v[90:93]
	v_mfma_f32_16x16x32_bf16 v[78:81], v[166:169], v[238:241], v[78:81]
	v_mfma_f32_16x16x32_bf16 v[74:77], v[174:177], v[238:241], v[74:77]
	v_mfma_f32_16x16x32_bf16 v[126:129], v[170:173], v[218:221], v[126:129]
	v_mfma_f32_16x16x32_bf16 v[122:125], v[194:197], v[218:221], v[122:125]
	v_mfma_f32_16x16x32_bf16 v[110:113], v[170:173], v[226:229], v[110:113]
	v_mfma_f32_16x16x32_bf16 v[106:109], v[194:197], v[226:229], v[106:109]
	v_mfma_f32_16x16x32_bf16 v[94:97], v[170:173], v[234:237], v[94:97]
	v_mfma_f32_16x16x32_bf16 v[90:93], v[194:197], v[234:237], v[90:93]
	v_mfma_f32_16x16x32_bf16 v[78:81], v[170:173], v[242:245], v[78:81]
	v_mfma_f32_16x16x32_bf16 v[74:77], v[194:197], v[242:245], v[74:77]
	v_mfma_f32_16x16x32_bf16 v[118:121], v[198:201], v[214:217], v[118:121]
	v_mfma_f32_16x16x32_bf16 v[114:117], v[206:209], v[214:217], v[114:117]
	v_mfma_f32_16x16x32_bf16 v[102:105], v[198:201], v[222:225], v[102:105]
	v_mfma_f32_16x16x32_bf16 v[98:101], v[206:209], v[222:225], v[98:101]
	v_mfma_f32_16x16x32_bf16 v[86:89], v[198:201], v[230:233], v[86:89]
	v_mfma_f32_16x16x32_bf16 v[82:85], v[206:209], v[230:233], v[82:85]
	v_mfma_f32_16x16x32_bf16 v[70:73], v[198:201], v[238:241], v[70:73]
	v_mfma_f32_16x16x32_bf16 v[66:69], v[206:209], v[238:241], v[66:69]
	v_mfma_f32_16x16x32_bf16 v[118:121], v[202:205], v[218:221], v[118:121]
	v_mfma_f32_16x16x32_bf16 v[114:117], v[210:213], v[218:221], v[114:117]
	v_mfma_f32_16x16x32_bf16 v[102:105], v[202:205], v[226:229], v[102:105]
	v_mfma_f32_16x16x32_bf16 v[98:101], v[210:213], v[226:229], v[98:101]
	v_mfma_f32_16x16x32_bf16 v[86:89], v[202:205], v[234:237], v[86:89]
	v_mfma_f32_16x16x32_bf16 v[82:85], v[210:213], v[234:237], v[82:85]
	v_mfma_f32_16x16x32_bf16 v[70:73], v[202:205], v[242:245], v[70:73]
	v_mfma_f32_16x16x32_bf16 v[66:69], v[210:213], v[242:245], v[66:69]
	s_barrier
; #define PG8_STAGE(bufoff, gbase, voff) do { _Pragma("unroll") for (int _i = 0; _i < 2; ++_i) \
;         __builtin_amdgcn_global_load_lds((const unsigned*)((const char*)(gbase) + (voff)[_i]), (PG8_LAS unsigned*)(lds + (bufoff) + ldsw + _i * 8192), 16, 0, 0); } while (0)
; #define PG8_LDA(dst, b, h) do { _Pragma("unroll") for (int m = 0; m < 4; ++m) _Pragma("unroll") for (int k = 0; k < 2; ++k) dst[m][k] = *(const PG8_LAS bf16x8*)(lds + PG8_SA(b, h) + aoff + m * 2048 + k * 1024); } while (0)
; #define PG8_MMA(ai, bj, At, Bt) do { __builtin_amdgcn_s_setprio(1); _Pragma("unroll") for (int m = 0; m < 4; ++m) _Pragma("unroll") for (int n = 0; n < 2; ++n) _Pragma("unroll") for (int k = 0; k < 2; ++k) \
;         acc[ai][bj][m][n] = __builtin_amdgcn_mfma_f32_16x16x32_bf16(Bt[n][k], At[m][k], acc[ai][bj][m][n], 0, 0, 0); __builtin_amdgcn_s_setprio(0); } while (0)
; #define PG8_WAIT_V(n) asm volatile("s_waitcnt vmcnt(" #n ")" ::: "memory")
; #define PG8_WAIT_L(n) asm volatile("s_waitcnt lgkmcnt(" #n ")" ::: "memory")
; #define PG8_BAR __builtin_amdgcn_s_barrier()
; #define PG8_SCHED __builtin_amdgcn_sched_barrier(0)
; template <class Epi, class Sched, bool ALIGN_EPI = false, bool SP2 = false>
; __device__ __forceinline__ void gemm_phase(PG8_LAS unsigned char* lds, const Gemm g, const Sched& S, const Epi& E, const int wv) {
;     ...
;             PG8_LDA(At, 1, 1); PG8_STAGE(PG8_SB(1, 0), b3, voffB); PG8_STAGE(PG8_SB(1, 1), b3 + hstep, voffB); PG8_STAGE(PG8_SA(1, 0), a3, voffA);
;             PG8_WAIT_V(8); PG8_WAIT_L(0); PG8_BAR; PG8_MMA(1, 0, At, B0); PG8_MMA(1, 1, At, B1); PG8_BAR; PG8_SCHED;
	s_setprio 0
	s_add_i32 s86, s89, s57
	v_lshl_add_u64 v[148:149], v[178:179], 0, s[26:27]
	s_mov_b32 m0, s86
	ds_read_b128 v[214:217], v192 offset:49152
	ds_read_b128 v[218:221], v192 offset:50176
	ds_read_b128 v[222:225], v192 offset:51200
	ds_read_b128 v[226:229], v192 offset:52224
	ds_read_b128 v[230:233], v192 offset:53248
	ds_read_b128 v[234:237], v192 offset:54272
	ds_read_b128 v[238:241], v192 offset:55296
	ds_read_b128 v[242:245], v192 offset:56320
	global_load_lds_dwordx4 v[148:149], off
	s_add_i32 m0, s86, 0x2000
	s_add_u32 s84, s84, 0x80080
	v_lshl_add_u64 v[148:149], v[246:247], 0, s[26:27]
	s_addc_u32 s85, s85, 0
	s_add_i32 s86, s90, s57
	global_load_lds_dwordx4 v[148:149], off
	v_lshl_add_u64 v[148:149], s[84:85], 0, v[132:133]
	s_mov_b32 m0, s86
	v_lshl_add_u64 v[146:147], v[146:147], 0, s[26:27]
	global_load_lds_dwordx4 v[148:149], off
	v_lshl_add_u64 v[148:149], s[84:85], 0, v[136:137]
	s_add_i32 m0, s86, 0x2000
	s_nop 0
	global_load_lds_dwordx4 v[148:149], off
	v_lshl_add_u64 v[148:149], v[248:249], 0, s[26:27]
	s_mov_b32 m0, s7
	s_nop 0
	global_load_lds_dwordx4 v[148:149], off
	s_mov_b32 m0, s22
	s_nop 0
	global_load_lds_dwordx4 v[146:147], off
	s_waitcnt vmcnt(8)
	s_waitcnt lgkmcnt(0)
	s_setprio 1
	s_barrier
	v_mfma_f32_16x16x32_bf16 v[62:65], v[166:169], v[214:217], v[62:65]
	v_mfma_f32_16x16x32_bf16 v[58:61], v[174:177], v[214:217], v[58:61]
	v_mfma_f32_16x16x32_bf16 v[46:49], v[166:169], v[222:225], v[46:49]
	v_mfma_f32_16x16x32_bf16 v[42:45], v[174:177], v[222:225], v[42:45]
	v_mfma_f32_16x16x32_bf16 v[30:33], v[166:169], v[230:233], v[30:33]
	v_mfma_f32_16x16x32_bf16 v[26:29], v[174:177], v[230:233], v[26:29]
	v_mfma_f32_16x16x32_bf16 v[14:17], v[166:169], v[238:241], v[14:17]
	v_mfma_f32_16x16x32_bf16 v[10:13], v[174:177], v[238:241], v[10:13]
	v_mfma_f32_16x16x32_bf16 v[62:65], v[170:173], v[218:221], v[62:65]
	v_mfma_f32_16x16x32_bf16 v[58:61], v[194:197], v[218:221], v[58:61]
	v_mfma_f32_16x16x32_bf16 v[46:49], v[170:173], v[226:229], v[46:49]
	v_mfma_f32_16x16x32_bf16 v[42:45], v[194:197], v[226:229], v[42:45]
	v_mfma_f32_16x16x32_bf16 v[30:33], v[170:173], v[234:237], v[30:33]
	v_mfma_f32_16x16x32_bf16 v[26:29], v[194:197], v[234:237], v[26:29]
	v_mfma_f32_16x16x32_bf16 v[14:17], v[170:173], v[242:245], v[14:17]
	v_mfma_f32_16x16x32_bf16 v[10:13], v[194:197], v[242:245], v[10:13]
	v_mfma_f32_16x16x32_bf16 v[54:57], v[198:201], v[214:217], v[54:57]
	v_mfma_f32_16x16x32_bf16 v[50:53], v[206:209], v[214:217], v[50:53]
	v_mfma_f32_16x16x32_bf16 v[38:41], v[198:201], v[222:225], v[38:41]
	v_mfma_f32_16x16x32_bf16 v[34:37], v[206:209], v[222:225], v[34:37]
	v_mfma_f32_16x16x32_bf16 v[22:25], v[198:201], v[230:233], v[22:25]
	v_mfma_f32_16x16x32_bf16 v[18:21], v[206:209], v[230:233], v[18:21]
	v_mfma_f32_16x16x32_bf16 v[6:9], v[198:201], v[238:241], v[6:9]
	v_mfma_f32_16x16x32_bf16 v[2:5], v[206:209], v[238:241], v[2:5]
	v_mfma_f32_16x16x32_bf16 v[54:57], v[202:205], v[218:221], v[54:57]
	v_mfma_f32_16x16x32_bf16 v[50:53], v[210:213], v[218:221], v[50:53]
	v_mfma_f32_16x16x32_bf16 v[38:41], v[202:205], v[226:229], v[38:41]
	v_mfma_f32_16x16x32_bf16 v[34:37], v[210:213], v[226:229], v[34:37]
	v_mfma_f32_16x16x32_bf16 v[22:25], v[202:205], v[234:237], v[22:25]
	v_mfma_f32_16x16x32_bf16 v[18:21], v[210:213], v[234:237], v[18:21]
	v_mfma_f32_16x16x32_bf16 v[6:9], v[202:205], v[242:245], v[6:9]
	v_mfma_f32_16x16x32_bf16 v[2:5], v[210:213], v[242:245], v[2:5]
	s_barrier
	s_setprio 0
	s_add_i32 s88, s88, 2
	s_add_u32 s77, s77, 0x100
	s_addc_u32 s83, s83, 0
	s_add_u32 s0, s0, 0x100
	s_addc_u32 s1, s1, 0
	s_cmp_gt_u32 s88, 29
	s_cbranch_scc0 .LBB0_957
	s_and_b64 vcc, exec, s[48:49]
	s_cbranch_vccz .LBB0_960
	s_barrier
